# plus sample-tile up-proj epilogue: one junk load per wave touches the 32 conv-state lines so the 32 serial state reads hit in cache
# speedup vs baseline: 1.0109x; 1.0028x over previous
; #define LAS __attribute__((address_space(3)))
;     template <bool SAMP, bool BND>
;     __device__ __forceinline__ void conv_act(const f32x4 (&acc)[2][2][4][2], const Unit& u, int wr, int fr, int rbase, int ccol, LAS float* halo, const LAS float* wl_) const {
;         unsigned char* wsb = (unsigned char*)karg(20);
;         bf16_t* ACT = (bf16_t*)(wsb + WS_ACT); const float* sffn = karg(5) + (size_t)l * SB * 2 * UPW; float* offp = (float*)karg(19) + O_FP + (size_t)l * NB * 2 * UPW;
;         u32x2 keep[2][4];
; #pragma unroll
;         for (int n = 0; n < 2; ++n) {
;             f32x4 W0[2], W1[2], W2[2], BB[2];
; #pragma unroll
;             for (int bj = 0; bj < 2; ++bj) {
;                 const int tc = bj * 128 + ccol + 4 * n;
;                 W0[bj] = *(const LAS f32x4*)(wl_ + tc); W1[bj] = *(const LAS f32x4*)(wl_ + 256 + tc); W2[bj] = *(const LAS f32x4*)(wl_ + 512 + tc); BB[bj] = *(const LAS f32x4*)(wl_ + 768 + tc);
;             }
; #pragma unroll
;             for (int ai = 0; ai < 2; ++ai)
; #pragma unroll
;                 for (int m = 0; m < 4; ++m) {
;                     const int row = rbase + 128 * ai + 16 * m + fr;
;                     const bool ok = SAMP || (row < NP && !(ai == 0 && m == 0 && wr == 0 && fr < 2));
;                     const int t4 = (row + 2) & 2047;
;                     const float z1 = (BND && t4 == 2) ? 0.f : 1.f, z2 = (BND && (t4 == 2 || t4 == 3)) ? 0.f : 1.f;
;                     f32x4 a[2];
; #pragma unroll
;                     for (int bj = 0; bj < 2; ++bj) {
;                         f32x4 prev;
;                         if (SAMP) { const int s = (rbase + 128 * ai + 16 * m - NP) >> 4; prev = *(const f32x4*)(sffn + (unsigned)((s * 2 + (fr & 1)) * UPW + bj * DFF + u.pn * 128 + ccol + 4 * n)); }
;                         else if (m > 0) prev = acc[ai][bj][m > 0 ? m - 1 : 0][n];
;                         else { const int blk = 2 * ai + wr; prev = (f32x4){0.f, 0.f, 0.f, 0.f}; if (blk > 0) prev = *(const LAS f32x4*)(halo + ((blk - 1) * 2 + (fr & 1)) * 256 + bj * 128 + ccol + 4 * n); }
;                         const f32x4 cur = acc[ai][bj][m][n];
; #pragma unroll
;                         for (int j = 0; j < 4; ++j) {
;                             const float p1 = dppf<0x111>(dppf<0x121>(0.f, prev[j]), cur[j]);
;                             const float p2 = dppf<0x112>(dppf<0x122>(0.f, prev[j]), cur[j]);
.LBB0_767:
	v_readlane_b32 s2, v255, 11
	v_readlane_b32 s3, v255, 12
	s_mov_b64 s[0:1], s[2:3]
	s_load_dwordx2 s[0:1], s[0:1], 0xa0
	v_readlane_b32 s6, v255, 30
	v_and_b32_e32 v215, 1, v195
	v_mov_b32_e32 v161, v189
	v_lshl_add_u32 v213, v188, 2, s31
	s_waitcnt lgkmcnt(0)
	s_add_u32 s4, s0, 0xaa00000
	s_addc_u32 s5, s1, 0
	s_mov_b64 s[0:1], s[2:3]
	s_load_dwordx2 s[0:1], s[0:1], 0x28
	v_mov_b32_e32 v168, v189
	v_mov_b32_e32 v174, v189
	v_mov_b32_e32 v170, v189
	v_mov_b32_e32 v172, v189
	s_waitcnt lgkmcnt(0)
	s_add_u32 s6, s0, s6
	s_addc_u32 s7, s1, s76
	s_mov_b64 s[0:1], s[2:3]
	s_add_i32 s0, s19, 0xffff8000
	s_lshr_b32 s0, s0, 3
	s_and_b32 s0, s0, 0x7ffffe
	v_or_b32_e32 v214, s0, v215
	s_movk_i32 s1, 0x1600
	v_mad_u32_u24 v164, v214, s1, v188
	s_lshl_b32 s3, s38, 7
	v_add_u32_e32 v160, s3, v164
	v_lshl_add_u64 v[160:161], v[160:161], 2, s[6:7]
	v_and_b32_e32 v242, 31, v208
	v_lshrrev_b32_e32 v243, 4, v242
	v_lshlrev_b32_e32 v243, 4, v243
	v_bfe_u32 v244, v242, 2, 2
	v_lshl_add_u32 v243, v244, 1, v243
	v_and_b32_e32 v244, 1, v242
	v_add3_u32 v243, v243, v244, s0
	v_bfe_u32 v244, v242, 1, 1
	v_mul_u32_u24_e32 v244, 0xb00, v244
	v_mad_u32_u24 v243, v243, s1, v244
	v_add_u32_e32 v242, s3, v243
	v_add_u32_e32 v242, s88, v242
	v_mov_b32_e32 v243, 0
	v_lshl_add_u64 v[242:243], v[242:243], 2, s[6:7]
	global_load_dword v244, v[242:243], off
	ds_read_b128 v[144:147], v213
	ds_read_b128 v[156:159], v213 offset:1024
	ds_read_b128 v[148:151], v213 offset:2048
	ds_read_b128 v[140:143], v213 offset:3072
	ds_read_b128 v[132:135], v213 offset:512
	ds_read_b128 v[152:155], v213 offset:1536
	ds_read_b128 v[136:139], v213 offset:2560
	ds_read_b128 v[128:131], v213 offset:3584
	global_load_dwordx4 v[160:163], v[160:161], off
	v_mov_b32_e32 v200, v189
	v_mov_b32_e32 v196, v189
	v_mov_b32_e32 v186, v189
	s_waitcnt vmcnt(0)
	v_mov_b32_dpp v168, v160 row_ror:1 row_mask:0xf bank_mask:0xf
	v_mov_b32_dpp v174, v160 row_ror:2 row_mask:0xf bank_mask:0xf
	v_mov_b32_e32 v160, v189
	v_mov_b32_dpp v170, v161 row_ror:1 row_mask:0xf bank_mask:0xf
	v_mov_b32_dpp v172, v161 row_ror:2 row_mask:0xf bank_mask:0xf
	v_mov_b32_dpp v160, v162 row_ror:1 row_mask:0xf bank_mask:0xf
	v_mov_b32_dpp v200, v162 row_ror:2 row_mask:0xf bank_mask:0xf
	v_mov_b32_dpp v196, v163 row_ror:1 row_mask:0xf bank_mask:0xf
	v_mov_b32_dpp v186, v163 row_ror:2 row_mask:0xf bank_mask:0xf
	v_mov_b32_dpp v168, v124 row_shr:1 row_mask:0xf bank_mask:0xf
	v_mov_b32_dpp v174, v124 row_shr:2 row_mask:0xf bank_mask:0xf
	v_mov_b32_dpp v170, v125 row_shr:1 row_mask:0xf bank_mask:0xf
	v_mov_b32_dpp v172, v125 row_shr:2 row_mask:0xf bank_mask:0xf
	v_mov_b32_dpp v160, v126 row_shr:1 row_mask:0xf bank_mask:0xf
	v_mov_b32_dpp v200, v126 row_shr:2 row_mask:0xf bank_mask:0xf
	v_mov_b32_dpp v196, v127 row_shr:1 row_mask:0xf bank_mask:0xf
	v_mov_b32_dpp v186, v127 row_shr:2 row_mask:0xf bank_mask:0xf
	s_add_i32 s2, s3, 0xb00
	v_add_u32_e32 v162, s2, v164
	v_mov_b32_e32 v163, v189
	v_lshl_add_u64 v[162:163], v[162:163], 2, s[6:7]
	global_load_dwordx4 v[216:219], v[162:163], off
	v_mov_b32_e32 v169, v189
	v_mov_b32_e32 v175, v189
	v_mov_b32_e32 v166, v124
	v_mov_b32_e32 v167, v120
	s_waitcnt lgkmcnt(5)
	v_mov_b32_e32 v162, v148
	s_waitcnt lgkmcnt(1)
	v_mov_b32_e32 v163, v136
	v_mov_b32_e32 v164, v140
	s_waitcnt lgkmcnt(0)
	v_mov_b32_e32 v165, v128
	v_pk_fma_f32 v[176:177], v[166:167], v[162:163], v[164:165]
	v_mov_b32_e32 v166, v156
	v_mov_b32_e32 v167, v152
	v_mov_b32_e32 v171, v189
	v_mov_b32_e32 v173, v189
	v_mov_b32_e32 v180, v157
	v_mov_b32_e32 v181, v153
	v_mov_b32_e32 v184, v145
	v_mov_b32_e32 v185, v133
	v_mov_b32_e32 v161, v189
	v_mov_b32_e32 v201, v189
	v_mov_b32_e32 v124, v126
	v_mov_b32_e32 v178, v158
	v_mov_b32_e32 v179, v154
	v_mov_b32_e32 v182, v146
	v_mov_b32_e32 v183, v134
	v_mov_b32_e32 v197, v189
	v_mov_b32_e32 v187, v189
	s_waitcnt vmcnt(0)
	v_mov_b32_dpp v169, v216 row_ror:1 row_mask:0xf bank_mask:0xf
	s_nop 1
	v_mov_b32_dpp v169, v120 row_shr:1 row_mask:0xf bank_mask:0xf
	v_mov_b32_dpp v175, v216 row_ror:2 row_mask:0xf bank_mask:0xf
	v_pk_fma_f32 v[176:177], v[166:167], v[168:169], v[176:177]
	v_mov_b32_e32 v168, v144
	v_mov_b32_dpp v175, v120 row_shr:2 row_mask:0xf bank_mask:0xf
	v_mov_b32_e32 v169, v132
	v_pk_fma_f32 v[198:199], v[168:169], v[174:175], v[176:177]
	v_mov_b32_dpp v171, v217 row_ror:1 row_mask:0xf bank_mask:0xf
	v_mov_b32_dpp v173, v217 row_ror:2 row_mask:0xf bank_mask:0xf
	v_mov_b32_e32 v120, v125
	v_mov_b32_e32 v174, v149
	v_mov_b32_e32 v175, v137
	v_mov_b32_e32 v176, v141
	v_mov_b32_e32 v177, v129
	v_mov_b32_dpp v171, v121 row_shr:1 row_mask:0xf bank_mask:0xf
	v_mov_b32_dpp v173, v121 row_shr:2 row_mask:0xf bank_mask:0xf
	v_pk_fma_f32 v[120:121], v[120:121], v[174:175], v[176:177]
	v_mov_b32_dpp v161, v218 row_ror:1 row_mask:0xf bank_mask:0xf
	v_pk_fma_f32 v[120:121], v[180:181], v[170:171], v[120:121]
	v_mov_b32_e32 v125, v122
	v_pk_fma_f32 v[120:121], v[184:185], v[172:173], v[120:121]
	v_mov_b32_e32 v170, v150
	v_mov_b32_e32 v171, v138
	v_mov_b32_e32 v172, v142
	v_mov_b32_e32 v173, v130
	v_mov_b32_dpp v161, v122 row_shr:1 row_mask:0xf bank_mask:0xf
	v_mov_b32_dpp v201, v218 row_ror:2 row_mask:0xf bank_mask:0xf
	v_pk_fma_f32 v[124:125], v[124:125], v[170:171], v[172:173]
	v_mov_b32_dpp v197, v219 row_ror:1 row_mask:0xf bank_mask:0xf
	v_mov_b32_dpp v201, v122 row_shr:2 row_mask:0xf bank_mask:0xf
	v_pk_fma_f32 v[124:125], v[178:179], v[160:161], v[124:125]
	v_mov_b32_dpp v187, v219 row_ror:2 row_mask:0xf bank_mask:0xf
	v_pk_fma_f32 v[200:201], v[182:183], v[200:201], v[124:125]
	v_mov_b32_e32 v122, v127
	v_mov_b32_e32 v124, v151
	v_mov_b32_e32 v125, v139
	v_mov_b32_e32 v160, v143
;     template <bool SAMP, bool BND>
;     __device__ __forceinline__ void conv_act(const f32x4 (&acc)[2][2][4][2], const Unit& u, int wr, int fr, int rbase, int ccol, LAS float* halo, const LAS float* wl_) const {
;     ...
;             for (int ai = 0; ai < 2; ++ai)
; #pragma unroll
;                 for (int m = 0; m < 4; ++m) {
;                     const int row = rbase + 128 * ai + 16 * m + fr;
;                     const bool ok = SAMP || (row < NP && !(ai == 0 && m == 0 && wr == 0 && fr < 2));
;                     const int t4 = (row + 2) & 2047;
;                     const float z1 = (BND && t4 == 2) ? 0.f : 1.f, z2 = (BND && (t4 == 2 || t4 == 3)) ? 0.f : 1.f;
;                     f32x4 a[2];
; #pragma unroll
;                     for (int bj = 0; bj < 2; ++bj) {
;                         f32x4 prev;
;                         if (SAMP) { const int s = (rbase + 128 * ai + 16 * m - NP) >> 4; prev = *(const f32x4*)(sffn + (unsigned)((s * 2 + (fr & 1)) * UPW + bj * DFF + u.pn * 128 + ccol + 4 * n)); }
;                         else if (m > 0) prev = acc[ai][bj][m > 0 ? m - 1 : 0][n];
;                         else { const int blk = 2 * ai + wr; prev = (f32x4){0.f, 0.f, 0.f, 0.f}; if (blk > 0) prev = *(const LAS f32x4*)(halo + ((blk - 1) * 2 + (fr & 1)) * 256 + bj * 128 + ccol + 4 * n); }
;                         const f32x4 cur = acc[ai][bj][m][n];
; #pragma unroll
;                         for (int j = 0; j < 4; ++j) {
;                             const float p1 = dppf<0x111>(dppf<0x121>(0.f, prev[j]), cur[j]);
;                             const float p2 = dppf<0x112>(dppf<0x122>(0.f, prev[j]), cur[j]);
;                             a[bj][j] = BB[bj][j] + W2[bj][j] * cur[j] + W1[bj][j] * (BND ? p1 * z1 : p1) + W0[bj][j] * (BND ? p2 * z2 : p2);
;                         }
;                         if (BND) { if (ok && t4 < 2 && row >= 2046) *(f32x4*)(offp + (unsigned)(((((row + 2) >> 11) - 1) * 2 + t4) * UPW + bj * DFF + u.pn * 128 + ccol + 4 * n)) = cur; }
;                         __builtin_amdgcn_sched_barrier(0);
;                     }
;                     float o[4];
; #pragma unroll
;                     for (int j = 0; j < 4; ++j) { const float g = a[0][j], v = a[1][j]; o[j] = g * __builtin_amdgcn_rcpf(1.0f + __builtin_amdgcn_exp2f(-g * LOG2E)) * v; }
;                     u32x2 w; w.x = cvt_pk_bf16(o[0], o[1]); w.y = cvt_pk_bf16(o[2], o[3]);
	v_mov_b32_e32 v161, v131
	v_mov_b32_dpp v197, v123 row_shr:1 row_mask:0xf bank_mask:0xf
	v_mov_b32_dpp v187, v123 row_shr:2 row_mask:0xf bank_mask:0xf
	v_pk_fma_f32 v[126:127], v[122:123], v[124:125], v[160:161]
	v_mov_b32_e32 v122, v159
	v_mov_b32_e32 v123, v155
	v_pk_fma_f32 v[196:197], v[122:123], v[196:197], v[126:127]
	v_mov_b32_e32 v126, v147
	v_mov_b32_e32 v127, v135
	v_pk_fma_f32 v[186:187], v[126:127], v[186:187], v[196:197]
	v_mul_f32_e32 v197, 0xbfb8aa3b, v120
	v_exp_f32_e32 v197, v197
	v_mul_f32_e32 v196, 0xbfb8aa3b, v198
	v_exp_f32_e32 v196, v196
	v_add_u32_e32 v195, s19, v195
	v_add_f32_e32 v197, 1.0, v197
	v_rcp_f32_e32 v197, v197
	v_add_f32_e32 v196, 1.0, v196
	v_rcp_f32_e32 v196, v196
	v_mul_f32_e32 v120, v120, v197
	v_mul_f32_e32 v120, v120, v121
	v_mul_f32_e32 v121, 0xbfb8aa3b, v200
	v_exp_f32_e32 v121, v121
	v_mul_f32_e32 v197, 0xbfb8aa3b, v186
	v_exp_f32_e32 v197, v197
	v_mul_f32_e32 v196, v198, v196
	v_add_f32_e32 v121, 1.0, v121
	v_rcp_f32_e32 v121, v121
	v_add_f32_e32 v197, 1.0, v197
	v_rcp_f32_e32 v197, v197
	v_mul_f32_e32 v196, v196, v199
	v_mul_f32_e32 v121, v200, v121
	v_mul_f32_e32 v121, v121, v201
	v_mul_f32_e32 v186, v186, v197
	v_mul_f32_e32 v186, v186, v187
	v_cvt_pk_bf16_f32 v120, v196, v120
	v_cvt_pk_bf16_f32 v121, v121, v186
	s_add_i32 s0, s19, 0xffff8010
	s_lshr_b32 s0, s0, 3
	s_and_b32 s0, s0, 0x7ffffe
	v_or_b32_e32 v198, s0, v215
	v_mad_u32_u24 v197, v198, s1, v188
	v_add_u32_e32 v186, s3, v197
	v_mov_b32_e32 v187, v189
	v_lshl_add_u64 v[186:187], v[186:187], 2, s[6:7]
	global_load_dwordx4 v[216:219], v[186:187], off
	v_mov_b32_e32 v200, v189
	v_mov_b32_e32 v204, v189
	v_mov_b32_e32 v220, v189
	v_mov_b32_e32 v222, v189
	v_mov_b32_e32 v224, v189
	v_mov_b32_e32 v226, v189
	v_mov_b32_e32 v186, v189
	v_mov_b32_e32 v196, v189
	s_waitcnt vmcnt(0)
	v_mov_b32_dpp v200, v216 row_ror:1 row_mask:0xf bank_mask:0xf
	v_mov_b32_dpp v204, v216 row_ror:2 row_mask:0xf bank_mask:0xf
	v_mov_b32_dpp v220, v217 row_ror:1 row_mask:0xf bank_mask:0xf
	v_mov_b32_dpp v222, v217 row_ror:2 row_mask:0xf bank_mask:0xf
	v_mov_b32_dpp v224, v218 row_ror:1 row_mask:0xf bank_mask:0xf
	v_mov_b32_dpp v226, v218 row_ror:2 row_mask:0xf bank_mask:0xf
	v_mov_b32_dpp v186, v219 row_ror:1 row_mask:0xf bank_mask:0xf
	v_mov_b32_dpp v196, v219 row_ror:2 row_mask:0xf bank_mask:0xf
	v_mov_b32_dpp v200, v112 row_shr:1 row_mask:0xf bank_mask:0xf
	v_mov_b32_dpp v204, v112 row_shr:2 row_mask:0xf bank_mask:0xf
	v_mov_b32_dpp v220, v113 row_shr:1 row_mask:0xf bank_mask:0xf
	v_mov_b32_dpp v222, v113 row_shr:2 row_mask:0xf bank_mask:0xf
	v_mov_b32_dpp v224, v114 row_shr:1 row_mask:0xf bank_mask:0xf
	v_mov_b32_dpp v226, v114 row_shr:2 row_mask:0xf bank_mask:0xf
	v_mov_b32_dpp v186, v115 row_shr:1 row_mask:0xf bank_mask:0xf
	v_mov_b32_dpp v196, v115 row_shr:2 row_mask:0xf bank_mask:0xf
	v_add_u32_e32 v216, s2, v197
	v_mov_b32_e32 v217, v189
	v_lshl_add_u64 v[216:217], v[216:217], 2, s[6:7]
	global_load_dwordx4 v[216:219], v[216:217], off
	v_mov_b32_e32 v201, v189
	v_mov_b32_e32 v205, v189
	v_mov_b32_e32 v221, v189
	v_mov_b32_e32 v223, v189
	v_mov_b32_e32 v225, v189
	v_mov_b32_e32 v227, v189
	v_mov_b32_e32 v229, v116
	v_mov_b32_e32 v187, v189
	v_mov_b32_e32 v228, v112
	v_mov_b32_e32 v197, v189
	v_pk_fma_f32 v[228:229], v[228:229], v[162:163], v[164:165]
	s_waitcnt vmcnt(0)
	v_mov_b32_dpp v201, v216 row_ror:1 row_mask:0xf bank_mask:0xf
	v_mov_b32_dpp v205, v216 row_ror:2 row_mask:0xf bank_mask:0xf
	s_nop 0
	v_mov_b32_dpp v201, v116 row_shr:1 row_mask:0xf bank_mask:0xf
	v_mov_b32_dpp v221, v217 row_ror:1 row_mask:0xf bank_mask:0xf
	v_mov_b32_dpp v205, v116 row_shr:2 row_mask:0xf bank_mask:0xf
	v_mov_b32_dpp v223, v217 row_ror:2 row_mask:0xf bank_mask:0xf
	v_mov_b32_e32 v116, v113
	v_mov_b32_dpp v225, v218 row_ror:1 row_mask:0xf bank_mask:0xf
	v_mov_b32_dpp v227, v218 row_ror:2 row_mask:0xf bank_mask:0xf
	v_mov_b32_dpp v221, v117 row_shr:1 row_mask:0xf bank_mask:0xf
	v_mov_b32_dpp v223, v117 row_shr:2 row_mask:0xf bank_mask:0xf
	v_pk_fma_f32 v[112:113], v[116:117], v[174:175], v[176:177]
	v_mov_b32_dpp v225, v118 row_shr:1 row_mask:0xf bank_mask:0xf
	v_mov_b32_dpp v227, v118 row_shr:2 row_mask:0xf bank_mask:0xf
	v_mov_b32_e32 v116, v114
	v_mov_b32_e32 v117, v118
	v_mov_b32_dpp v187, v219 row_ror:1 row_mask:0xf bank_mask:0xf
	v_mov_b32_e32 v118, v115
	v_pk_fma_f32 v[116:117], v[116:117], v[170:171], v[172:173]
	v_mov_b32_dpp v187, v119 row_shr:1 row_mask:0xf bank_mask:0xf
	v_mov_b32_dpp v197, v219 row_ror:2 row_mask:0xf bank_mask:0xf
	v_pk_fma_f32 v[114:115], v[118:119], v[124:125], v[160:161]
	v_pk_fma_f32 v[200:201], v[166:167], v[200:201], v[228:229]
	v_pk_fma_f32 v[112:113], v[180:181], v[220:221], v[112:113]
	v_pk_fma_f32 v[116:117], v[178:179], v[224:225], v[116:117]
	v_mov_b32_dpp v197, v119 row_shr:2 row_mask:0xf bank_mask:0xf
	v_pk_fma_f32 v[114:115], v[122:123], v[186:187], v[114:115]
	v_pk_fma_f32 v[200:201], v[168:169], v[204:205], v[200:201]
	v_pk_fma_f32 v[112:113], v[184:185], v[222:223], v[112:113]
	v_pk_fma_f32 v[116:117], v[182:183], v[226:227], v[116:117]
	v_pk_fma_f32 v[114:115], v[126:127], v[196:197], v[114:115]
	v_mul_f32_e32 v119, 0xbfb8aa3b, v112
	v_exp_f32_e32 v119, v119
	v_mul_f32_e32 v118, 0xbfb8aa3b, v200
	v_exp_f32_e32 v118, v118
	v_add_f32_e32 v119, 1.0, v119
	v_rcp_f32_e32 v119, v119
	v_add_f32_e32 v118, 1.0, v118
	v_rcp_f32_e32 v118, v118
	v_mul_f32_e32 v112, v112, v119
	v_mul_f32_e32 v112, v112, v113
	v_mul_f32_e32 v113, 0xbfb8aa3b, v116
	v_exp_f32_e32 v113, v113
	v_mul_f32_e32 v118, v200, v118
	v_mul_f32_e32 v118, v118, v201
	v_cvt_pk_bf16_f32 v112, v118, v112
	v_add_f32_e32 v113, 1.0, v113
	v_rcp_f32_e32 v113, v113
	s_nop 0
	v_mul_f32_e32 v113, v116, v113
	v_mul_f32_e32 v116, 0xbfb8aa3b, v114
	v_exp_f32_e32 v116, v116
	v_mul_f32_e32 v113, v113, v117
	v_add_f32_e32 v116, 1.0, v116
	v_rcp_f32_e32 v116, v116
	s_nop 0
	v_mul_f32_e32 v114, v114, v116
	v_mul_f32_e32 v114, v114, v115
	v_cvt_pk_bf16_f32 v113, v113, v114
	s_add_i32 s0, s19, 0xffff8020
	s_lshr_b32 s0, s0, 3
	s_and_b32 s0, s0, 0x7ffffe
	v_or_b32_e32 v187, s0, v215
	v_mad_u32_u24 v119, v187, s1, v188
	v_add_u32_e32 v114, s3, v119
	v_mov_b32_e32 v115, v189
	v_lshl_add_u64 v[114:115], v[114:115], 2, s[6:7]
	global_load_dwordx4 v[114:117], v[114:115], off
	v_mov_b32_e32 v118, v189
	v_mov_b32_e32 v196, v189
	v_mov_b32_e32 v220, v189
	v_mov_b32_e32 v222, v189
	v_mov_b32_e32 v200, v189
	v_mov_b32_e32 v204, v189
	s_waitcnt vmcnt(0)
;     template <bool SAMP, bool BND>
;     __device__ __forceinline__ void conv_act(const f32x4 (&acc)[2][2][4][2], const Unit& u, int wr, int fr, int rbase, int ccol, LAS float* halo, const LAS float* wl_) const {
;     ...
;             for (int ai = 0; ai < 2; ++ai)
; #pragma unroll
;                 for (int m = 0; m < 4; ++m) {
;                     const int row = rbase + 128 * ai + 16 * m + fr;
;                     const bool ok = SAMP || (row < NP && !(ai == 0 && m == 0 && wr == 0 && fr < 2));
;                     const int t4 = (row + 2) & 2047;
;                     const float z1 = (BND && t4 == 2) ? 0.f : 1.f, z2 = (BND && (t4 == 2 || t4 == 3)) ? 0.f : 1.f;
;                     f32x4 a[2];
; #pragma unroll
;                     for (int bj = 0; bj < 2; ++bj) {
;                         f32x4 prev;
;                         if (SAMP) { const int s = (rbase + 128 * ai + 16 * m - NP) >> 4; prev = *(const f32x4*)(sffn + (unsigned)((s * 2 + (fr & 1)) * UPW + bj * DFF + u.pn * 128 + ccol + 4 * n)); }
;                         else if (m > 0) prev = acc[ai][bj][m > 0 ? m - 1 : 0][n];
;                         else { const int blk = 2 * ai + wr; prev = (f32x4){0.f, 0.f, 0.f, 0.f}; if (blk > 0) prev = *(const LAS f32x4*)(halo + ((blk - 1) * 2 + (fr & 1)) * 256 + bj * 128 + ccol + 4 * n); }
;                         const f32x4 cur = acc[ai][bj][m][n];
; #pragma unroll
;                         for (int j = 0; j < 4; ++j) {
;                             const float p1 = dppf<0x111>(dppf<0x121>(0.f, prev[j]), cur[j]);
;                             const float p2 = dppf<0x112>(dppf<0x122>(0.f, prev[j]), cur[j]);
;                             a[bj][j] = BB[bj][j] + W2[bj][j] * cur[j] + W1[bj][j] * (BND ? p1 * z1 : p1) + W0[bj][j] * (BND ? p2 * z2 : p2);
;                         }
;                         if (BND) { if (ok && t4 < 2 && row >= 2046) *(f32x4*)(offp + (unsigned)(((((row + 2) >> 11) - 1) * 2 + t4) * UPW + bj * DFF + u.pn * 128 + ccol + 4 * n)) = cur; }
;                         __builtin_amdgcn_sched_barrier(0);
;                     }
;                     float o[4];
; #pragma unroll
;                     for (int j = 0; j < 4; ++j) { const float g = a[0][j], v = a[1][j]; o[j] = g * __builtin_amdgcn_rcpf(1.0f + __builtin_amdgcn_exp2f(-g * LOG2E)) * v; }
;                     u32x2 w; w.x = cvt_pk_bf16(o[0], o[1]); w.y = cvt_pk_bf16(o[2], o[3]);
	v_mov_b32_dpp v118, v114 row_ror:1 row_mask:0xf bank_mask:0xf
	v_mov_b32_dpp v196, v114 row_ror:2 row_mask:0xf bank_mask:0xf
	v_mov_b32_dpp v220, v116 row_ror:1 row_mask:0xf bank_mask:0xf
	v_mov_b32_dpp v222, v116 row_ror:2 row_mask:0xf bank_mask:0xf
	v_mov_b32_e32 v114, v189
	v_mov_b32_e32 v116, v189
	v_mov_b32_dpp v200, v115 row_ror:1 row_mask:0xf bank_mask:0xf
	v_mov_b32_dpp v204, v115 row_ror:2 row_mask:0xf bank_mask:0xf
	v_mov_b32_dpp v114, v117 row_ror:1 row_mask:0xf bank_mask:0xf
	v_mov_b32_dpp v116, v117 row_ror:2 row_mask:0xf bank_mask:0xf
	v_mov_b32_dpp v118, v104 row_shr:1 row_mask:0xf bank_mask:0xf
	v_mov_b32_dpp v196, v104 row_shr:2 row_mask:0xf bank_mask:0xf
	v_mov_b32_dpp v200, v105 row_shr:1 row_mask:0xf bank_mask:0xf
	v_mov_b32_dpp v204, v105 row_shr:2 row_mask:0xf bank_mask:0xf
	v_mov_b32_dpp v220, v106 row_shr:1 row_mask:0xf bank_mask:0xf
	v_mov_b32_dpp v222, v106 row_shr:2 row_mask:0xf bank_mask:0xf
	v_mov_b32_dpp v114, v107 row_shr:1 row_mask:0xf bank_mask:0xf
	v_mov_b32_dpp v116, v107 row_shr:2 row_mask:0xf bank_mask:0xf
	v_add_u32_e32 v216, s2, v119
	v_mov_b32_e32 v217, v189
	v_lshl_add_u64 v[216:217], v[216:217], 2, s[6:7]
	global_load_dwordx4 v[216:219], v[216:217], off
	v_mov_b32_e32 v119, v189
	v_mov_b32_e32 v197, v189
	v_mov_b32_e32 v201, v189
	v_mov_b32_e32 v205, v189
	v_mov_b32_e32 v221, v189
	v_mov_b32_e32 v223, v189
	v_mov_b32_e32 v225, v108
	v_mov_b32_e32 v115, v189
	v_mov_b32_e32 v224, v104
	v_mov_b32_e32 v117, v189
	v_pk_fma_f32 v[224:225], v[224:225], v[162:163], v[164:165]
	s_waitcnt vmcnt(0)
	v_mov_b32_dpp v119, v216 row_ror:1 row_mask:0xf bank_mask:0xf
	v_mov_b32_dpp v197, v216 row_ror:2 row_mask:0xf bank_mask:0xf
	s_nop 0
	v_mov_b32_dpp v119, v108 row_shr:1 row_mask:0xf bank_mask:0xf
	v_mov_b32_dpp v201, v217 row_ror:1 row_mask:0xf bank_mask:0xf
	v_mov_b32_dpp v197, v108 row_shr:2 row_mask:0xf bank_mask:0xf
	v_mov_b32_dpp v205, v217 row_ror:2 row_mask:0xf bank_mask:0xf
	v_mov_b32_e32 v108, v105
	v_mov_b32_dpp v221, v218 row_ror:1 row_mask:0xf bank_mask:0xf
	v_mov_b32_dpp v223, v218 row_ror:2 row_mask:0xf bank_mask:0xf
	v_mov_b32_dpp v201, v109 row_shr:1 row_mask:0xf bank_mask:0xf
	v_mov_b32_dpp v205, v109 row_shr:2 row_mask:0xf bank_mask:0xf
	v_pk_fma_f32 v[104:105], v[108:109], v[174:175], v[176:177]
	v_mov_b32_dpp v221, v110 row_shr:1 row_mask:0xf bank_mask:0xf
	v_mov_b32_dpp v223, v110 row_shr:2 row_mask:0xf bank_mask:0xf
	v_mov_b32_e32 v108, v106
	v_mov_b32_e32 v109, v110
	v_mov_b32_dpp v115, v219 row_ror:1 row_mask:0xf bank_mask:0xf
	v_mov_b32_e32 v110, v107
	v_pk_fma_f32 v[108:109], v[108:109], v[170:171], v[172:173]
	v_mov_b32_dpp v115, v111 row_shr:1 row_mask:0xf bank_mask:0xf
	v_mov_b32_dpp v117, v219 row_ror:2 row_mask:0xf bank_mask:0xf
	v_pk_fma_f32 v[106:107], v[110:111], v[124:125], v[160:161]
	v_pk_fma_f32 v[118:119], v[166:167], v[118:119], v[224:225]
	v_pk_fma_f32 v[104:105], v[180:181], v[200:201], v[104:105]
	v_pk_fma_f32 v[108:109], v[178:179], v[220:221], v[108:109]
	v_mov_b32_dpp v117, v111 row_shr:2 row_mask:0xf bank_mask:0xf
	v_pk_fma_f32 v[106:107], v[122:123], v[114:115], v[106:107]
	v_pk_fma_f32 v[118:119], v[168:169], v[196:197], v[118:119]
	v_pk_fma_f32 v[104:105], v[184:185], v[204:205], v[104:105]
	v_pk_fma_f32 v[108:109], v[182:183], v[222:223], v[108:109]
	v_pk_fma_f32 v[106:107], v[126:127], v[116:117], v[106:107]
	v_mul_f32_e32 v111, 0xbfb8aa3b, v104
	v_exp_f32_e32 v111, v111
	v_mul_f32_e32 v110, 0xbfb8aa3b, v118
	v_exp_f32_e32 v110, v110
	v_add_f32_e32 v111, 1.0, v111
	v_rcp_f32_e32 v111, v111
	v_add_f32_e32 v110, 1.0, v110
	v_rcp_f32_e32 v110, v110
	v_mul_f32_e32 v104, v104, v111
	v_mul_f32_e32 v104, v104, v105
	v_mul_f32_e32 v105, 0xbfb8aa3b, v108
	v_exp_f32_e32 v105, v105
	v_mul_f32_e32 v110, v118, v110
	v_mul_f32_e32 v110, v110, v119
	v_cvt_pk_bf16_f32 v104, v110, v104
	v_add_f32_e32 v105, 1.0, v105
	v_rcp_f32_e32 v105, v105
	s_nop 0
	v_mul_f32_e32 v105, v108, v105
	v_mul_f32_e32 v108, 0xbfb8aa3b, v106
	v_exp_f32_e32 v108, v108
	v_mul_f32_e32 v105, v105, v109
	v_add_f32_e32 v108, 1.0, v108
	v_rcp_f32_e32 v108, v108
	s_nop 0
	v_mul_f32_e32 v106, v106, v108
	v_mul_f32_e32 v106, v106, v107
	v_cvt_pk_bf16_f32 v105, v105, v106
	s_add_i32 s0, s19, 0xffff8030
	s_lshr_b32 s0, s0, 3
	s_and_b32 s0, s0, 0x7ffffe
	v_or_b32_e32 v186, s0, v215
	v_mad_u32_u24 v111, v186, s1, v188
	v_add_u32_e32 v106, s3, v111
	v_mov_b32_e32 v107, v189
	v_lshl_add_u64 v[106:107], v[106:107], 2, s[6:7]
	global_load_dwordx4 v[106:109], v[106:107], off
	v_mov_b32_e32 v110, v189
	v_mov_b32_e32 v118, v189
	v_mov_b32_e32 v204, v189
	v_mov_b32_e32 v216, v189
	v_mov_b32_e32 v196, v189
	v_mov_b32_e32 v200, v189
	s_waitcnt vmcnt(0)
	v_mov_b32_dpp v110, v106 row_ror:1 row_mask:0xf bank_mask:0xf
	v_mov_b32_dpp v118, v106 row_ror:2 row_mask:0xf bank_mask:0xf
	v_mov_b32_dpp v204, v108 row_ror:1 row_mask:0xf bank_mask:0xf
	v_mov_b32_dpp v216, v108 row_ror:2 row_mask:0xf bank_mask:0xf
	v_mov_b32_e32 v106, v189
	v_mov_b32_e32 v108, v189
	v_mov_b32_dpp v196, v107 row_ror:1 row_mask:0xf bank_mask:0xf
	v_mov_b32_dpp v200, v107 row_ror:2 row_mask:0xf bank_mask:0xf
	v_mov_b32_dpp v106, v109 row_ror:1 row_mask:0xf bank_mask:0xf
	v_mov_b32_dpp v108, v109 row_ror:2 row_mask:0xf bank_mask:0xf
	v_mov_b32_dpp v110, v96 row_shr:1 row_mask:0xf bank_mask:0xf
	v_mov_b32_dpp v118, v96 row_shr:2 row_mask:0xf bank_mask:0xf
	v_mov_b32_dpp v196, v97 row_shr:1 row_mask:0xf bank_mask:0xf
	v_mov_b32_dpp v200, v97 row_shr:2 row_mask:0xf bank_mask:0xf
	v_mov_b32_dpp v204, v98 row_shr:1 row_mask:0xf bank_mask:0xf
	v_mov_b32_dpp v216, v98 row_shr:2 row_mask:0xf bank_mask:0xf
	v_mov_b32_dpp v106, v99 row_shr:1 row_mask:0xf bank_mask:0xf
	v_mov_b32_dpp v108, v99 row_shr:2 row_mask:0xf bank_mask:0xf
	v_add_u32_e32 v114, s2, v111
	v_mov_b32_e32 v115, v189
	v_lshl_add_u64 v[114:115], v[114:115], 2, s[6:7]
	global_load_dwordx4 v[114:117], v[114:115], off
	v_mov_b32_e32 v111, v189
	v_mov_b32_e32 v119, v189
	v_mov_b32_e32 v197, v189
	v_mov_b32_e32 v201, v189
	v_mov_b32_e32 v205, v189
	v_mov_b32_e32 v217, v189
	v_mov_b32_e32 v219, v100
	v_mov_b32_e32 v107, v189
	v_mov_b32_e32 v218, v96
	v_mov_b32_e32 v109, v189
	v_pk_fma_f32 v[162:163], v[218:219], v[162:163], v[164:165]
	s_waitcnt vmcnt(0)
;     template <bool SAMP, bool BND>
;     __device__ __forceinline__ void conv_act(const f32x4 (&acc)[2][2][4][2], const Unit& u, int wr, int fr, int rbase, int ccol, LAS float* halo, const LAS float* wl_) const {
;     ...
;             for (int ai = 0; ai < 2; ++ai)
; #pragma unroll
;                 for (int m = 0; m < 4; ++m) {
;                     const int row = rbase + 128 * ai + 16 * m + fr;
;                     const bool ok = SAMP || (row < NP && !(ai == 0 && m == 0 && wr == 0 && fr < 2));
;                     const int t4 = (row + 2) & 2047;
;                     const float z1 = (BND && t4 == 2) ? 0.f : 1.f, z2 = (BND && (t4 == 2 || t4 == 3)) ? 0.f : 1.f;
;                     f32x4 a[2];
; #pragma unroll
;                     for (int bj = 0; bj < 2; ++bj) {
;                         f32x4 prev;
;                         if (SAMP) { const int s = (rbase + 128 * ai + 16 * m - NP) >> 4; prev = *(const f32x4*)(sffn + (unsigned)((s * 2 + (fr & 1)) * UPW + bj * DFF + u.pn * 128 + ccol + 4 * n)); }
;                         else if (m > 0) prev = acc[ai][bj][m > 0 ? m - 1 : 0][n];
;                         else { const int blk = 2 * ai + wr; prev = (f32x4){0.f, 0.f, 0.f, 0.f}; if (blk > 0) prev = *(const LAS f32x4*)(halo + ((blk - 1) * 2 + (fr & 1)) * 256 + bj * 128 + ccol + 4 * n); }
;                         const f32x4 cur = acc[ai][bj][m][n];
; #pragma unroll
;                         for (int j = 0; j < 4; ++j) {
;                             const float p1 = dppf<0x111>(dppf<0x121>(0.f, prev[j]), cur[j]);
;                             const float p2 = dppf<0x112>(dppf<0x122>(0.f, prev[j]), cur[j]);
;                             a[bj][j] = BB[bj][j] + W2[bj][j] * cur[j] + W1[bj][j] * (BND ? p1 * z1 : p1) + W0[bj][j] * (BND ? p2 * z2 : p2);
;                         }
;                         if (BND) { if (ok && t4 < 2 && row >= 2046) *(f32x4*)(offp + (unsigned)(((((row + 2) >> 11) - 1) * 2 + t4) * UPW + bj * DFF + u.pn * 128 + ccol + 4 * n)) = cur; }
;                         __builtin_amdgcn_sched_barrier(0);
;                     }
;                     float o[4];
; #pragma unroll
;                     for (int j = 0; j < 4; ++j) { const float g = a[0][j], v = a[1][j]; o[j] = g * __builtin_amdgcn_rcpf(1.0f + __builtin_amdgcn_exp2f(-g * LOG2E)) * v; }
;                     u32x2 w; w.x = cvt_pk_bf16(o[0], o[1]); w.y = cvt_pk_bf16(o[2], o[3]);
	v_mov_b32_dpp v111, v114 row_ror:1 row_mask:0xf bank_mask:0xf
	v_mov_b32_dpp v119, v114 row_ror:2 row_mask:0xf bank_mask:0xf
	s_nop 0
	v_mov_b32_dpp v111, v100 row_shr:1 row_mask:0xf bank_mask:0xf
	v_mov_b32_dpp v197, v115 row_ror:1 row_mask:0xf bank_mask:0xf
	v_mov_b32_dpp v119, v100 row_shr:2 row_mask:0xf bank_mask:0xf
	v_mov_b32_dpp v201, v115 row_ror:2 row_mask:0xf bank_mask:0xf
	v_mov_b32_e32 v100, v97
	v_mov_b32_dpp v205, v116 row_ror:1 row_mask:0xf bank_mask:0xf
	v_mov_b32_dpp v217, v116 row_ror:2 row_mask:0xf bank_mask:0xf
	v_mov_b32_dpp v197, v101 row_shr:1 row_mask:0xf bank_mask:0xf
	v_mov_b32_dpp v201, v101 row_shr:2 row_mask:0xf bank_mask:0xf
	v_pk_fma_f32 v[96:97], v[100:101], v[174:175], v[176:177]
	v_mov_b32_dpp v205, v102 row_shr:1 row_mask:0xf bank_mask:0xf
	v_mov_b32_dpp v217, v102 row_shr:2 row_mask:0xf bank_mask:0xf
	v_mov_b32_e32 v100, v98
	v_mov_b32_e32 v101, v102
	v_mov_b32_dpp v107, v117 row_ror:1 row_mask:0xf bank_mask:0xf
	v_mov_b32_e32 v102, v99
	v_pk_fma_f32 v[100:101], v[100:101], v[170:171], v[172:173]
	v_mov_b32_dpp v107, v103 row_shr:1 row_mask:0xf bank_mask:0xf
	v_mov_b32_dpp v109, v117 row_ror:2 row_mask:0xf bank_mask:0xf
	v_pk_fma_f32 v[98:99], v[102:103], v[124:125], v[160:161]
	v_pk_fma_f32 v[110:111], v[166:167], v[110:111], v[162:163]
	v_pk_fma_f32 v[96:97], v[180:181], v[196:197], v[96:97]
	v_pk_fma_f32 v[100:101], v[178:179], v[204:205], v[100:101]
	v_mov_b32_dpp v109, v103 row_shr:2 row_mask:0xf bank_mask:0xf
	v_pk_fma_f32 v[98:99], v[122:123], v[106:107], v[98:99]
	v_pk_fma_f32 v[110:111], v[168:169], v[118:119], v[110:111]
	v_pk_fma_f32 v[96:97], v[184:185], v[200:201], v[96:97]
	v_pk_fma_f32 v[100:101], v[182:183], v[216:217], v[100:101]
	v_pk_fma_f32 v[98:99], v[126:127], v[108:109], v[98:99]
	v_mul_f32_e32 v103, 0xbfb8aa3b, v96
	v_exp_f32_e32 v103, v103
	v_mul_f32_e32 v102, 0xbfb8aa3b, v110
	v_exp_f32_e32 v102, v102
	v_add_f32_e32 v103, 1.0, v103
	v_rcp_f32_e32 v103, v103
	v_add_f32_e32 v102, 1.0, v102
	v_rcp_f32_e32 v102, v102
	v_mul_f32_e32 v96, v96, v103
	v_mul_f32_e32 v96, v96, v97
	v_mul_f32_e32 v97, 0xbfb8aa3b, v100
	v_exp_f32_e32 v97, v97
	v_mul_f32_e32 v102, v110, v102
	v_mul_f32_e32 v102, v102, v111
	v_cvt_pk_bf16_f32 v96, v102, v96
	v_add_f32_e32 v97, 1.0, v97
	v_rcp_f32_e32 v97, v97
	s_nop 0
	v_mul_f32_e32 v97, v100, v97
	v_mul_f32_e32 v100, 0xbfb8aa3b, v98
	v_exp_f32_e32 v100, v100
	v_mul_f32_e32 v97, v97, v101
	v_add_f32_e32 v100, 1.0, v100
	v_rcp_f32_e32 v100, v100
	s_nop 0
	v_mul_f32_e32 v98, v98, v100
	v_mul_f32_e32 v98, v98, v99
	v_cvt_pk_bf16_f32 v97, v97, v98
	s_add_i32 s0, s19, 0xffff8080
	s_lshr_b32 s0, s0, 3
	s_and_b32 s0, s0, 0x7ffffe
	v_or_b32_e32 v160, s0, v215
	v_mad_u32_u24 v108, v160, s1, v188
	v_add_u32_e32 v98, s3, v108
	v_mov_b32_e32 v99, v189
	v_lshl_add_u64 v[98:99], v[98:99], 2, s[6:7]
	global_load_dwordx4 v[100:103], v[98:99], off
	v_mov_b32_e32 v106, v189
	v_mov_b32_e32 v107, v189
	v_mov_b32_e32 v98, v156
	v_mov_b32_e32 v99, v144
	v_mov_b32_e32 v144, v157
	s_waitcnt vmcnt(0)
	v_mov_b32_dpp v106, v100 row_ror:1 row_mask:0xf bank_mask:0xf
	v_mov_b32_dpp v107, v100 row_ror:2 row_mask:0xf bank_mask:0xf
	s_nop 0
	v_mov_b32_dpp v106, v92 row_shr:1 row_mask:0xf bank_mask:0xf
	v_fma_f32 v100, v93, v149, v141
	v_mov_b32_dpp v107, v92 row_shr:2 row_mask:0xf bank_mask:0xf
	v_fma_f32 v92, v92, v148, v140
	v_pk_mul_f32 v[106:107], v[98:99], v[106:107]
	s_nop 0
	v_add_f32_e32 v92, v92, v106
	v_add_f32_e32 v109, v92, v107
	v_mov_b32_e32 v106, v189
	v_mov_b32_e32 v107, v189
	s_nop 0
	v_mov_b32_dpp v106, v101 row_ror:1 row_mask:0xf bank_mask:0xf
	v_mov_b32_dpp v107, v101 row_ror:2 row_mask:0xf bank_mask:0xf
	v_mov_b32_e32 v101, v189
	v_mov_b32_dpp v106, v93 row_shr:1 row_mask:0xf bank_mask:0xf
	v_mov_b32_dpp v107, v93 row_shr:2 row_mask:0xf bank_mask:0xf
	v_pk_mul_f32 v[92:93], v[144:145], v[106:107]
	v_mov_b32_dpp v101, v102 row_ror:2 row_mask:0xf bank_mask:0xf
	v_add_f32_e32 v92, v100, v92
	v_mov_b32_e32 v100, v189
	v_add_f32_e32 v110, v92, v93
	v_mov_b32_dpp v101, v94 row_shr:2 row_mask:0xf bank_mask:0xf
	v_mov_b32_dpp v100, v102 row_ror:1 row_mask:0xf bank_mask:0xf
	v_mov_b32_e32 v92, v158
	v_mov_b32_e32 v93, v146
	v_mov_b32_dpp v100, v94 row_shr:1 row_mask:0xf bank_mask:0xf
	v_fma_f32 v94, v94, v150, v142
	v_pk_mul_f32 v[100:101], v[92:93], v[100:101]
	v_mov_b32_e32 v146, v159
	v_add_f32_e32 v94, v94, v100
	v_add_f32_e32 v111, v94, v101
	v_mov_b32_e32 v100, v189
	v_mov_b32_e32 v101, v189
	v_fma_f32 v102, v95, v151, v143
	v_mov_b32_dpp v100, v103 row_ror:1 row_mask:0xf bank_mask:0xf
	v_mov_b32_dpp v101, v103 row_ror:2 row_mask:0xf bank_mask:0xf
	s_nop 0
	v_mov_b32_dpp v100, v95 row_shr:1 row_mask:0xf bank_mask:0xf
	v_mov_b32_dpp v101, v95 row_shr:2 row_mask:0xf bank_mask:0xf
	v_pk_mul_f32 v[94:95], v[146:147], v[100:101]
	s_nop 0
	v_add_f32_e32 v94, v102, v94
	v_add_f32_e32 v114, v94, v95
	v_add_u32_e32 v94, s2, v108
	v_mov_b32_e32 v95, v189
	v_lshl_add_u64 v[94:95], v[94:95], 2, s[6:7]
	global_load_dwordx4 v[100:103], v[94:95], off
	v_mov_b32_e32 v106, v189
	v_mov_b32_e32 v107, v189
	v_mov_b32_e32 v94, v152
	v_mov_b32_e32 v95, v132
	v_mov_b32_e32 v132, v153
	s_waitcnt vmcnt(0)
;     template <bool SAMP, bool BND>
;     __device__ __forceinline__ void conv_act(const f32x4 (&acc)[2][2][4][2], const Unit& u, int wr, int fr, int rbase, int ccol, LAS float* halo, const LAS float* wl_) const {
;     ...
;             for (int ai = 0; ai < 2; ++ai)
; #pragma unroll
;                 for (int m = 0; m < 4; ++m) {
;                     const int row = rbase + 128 * ai + 16 * m + fr;
;                     const bool ok = SAMP || (row < NP && !(ai == 0 && m == 0 && wr == 0 && fr < 2));
;                     const int t4 = (row + 2) & 2047;
;                     const float z1 = (BND && t4 == 2) ? 0.f : 1.f, z2 = (BND && (t4 == 2 || t4 == 3)) ? 0.f : 1.f;
;                     f32x4 a[2];
; #pragma unroll
;                     for (int bj = 0; bj < 2; ++bj) {
;                         f32x4 prev;
;                         if (SAMP) { const int s = (rbase + 128 * ai + 16 * m - NP) >> 4; prev = *(const f32x4*)(sffn + (unsigned)((s * 2 + (fr & 1)) * UPW + bj * DFF + u.pn * 128 + ccol + 4 * n)); }
;                         else if (m > 0) prev = acc[ai][bj][m > 0 ? m - 1 : 0][n];
;                         else { const int blk = 2 * ai + wr; prev = (f32x4){0.f, 0.f, 0.f, 0.f}; if (blk > 0) prev = *(const LAS f32x4*)(halo + ((blk - 1) * 2 + (fr & 1)) * 256 + bj * 128 + ccol + 4 * n); }
;                         const f32x4 cur = acc[ai][bj][m][n];
; #pragma unroll
;                         for (int j = 0; j < 4; ++j) {
;                             const float p1 = dppf<0x111>(dppf<0x121>(0.f, prev[j]), cur[j]);
;                             const float p2 = dppf<0x112>(dppf<0x122>(0.f, prev[j]), cur[j]);
;                             a[bj][j] = BB[bj][j] + W2[bj][j] * cur[j] + W1[bj][j] * (BND ? p1 * z1 : p1) + W0[bj][j] * (BND ? p2 * z2 : p2);
;                         }
;                         if (BND) { if (ok && t4 < 2 && row >= 2046) *(f32x4*)(offp + (unsigned)(((((row + 2) >> 11) - 1) * 2 + t4) * UPW + bj * DFF + u.pn * 128 + ccol + 4 * n)) = cur; }
;                         __builtin_amdgcn_sched_barrier(0);
;                     }
;                     float o[4];
; #pragma unroll
;                     for (int j = 0; j < 4; ++j) { const float g = a[0][j], v = a[1][j]; o[j] = g * __builtin_amdgcn_rcpf(1.0f + __builtin_amdgcn_exp2f(-g * LOG2E)) * v; }
;                     u32x2 w; w.x = cvt_pk_bf16(o[0], o[1]); w.y = cvt_pk_bf16(o[2], o[3]);
	v_mov_b32_dpp v106, v100 row_ror:1 row_mask:0xf bank_mask:0xf
	v_mov_b32_dpp v107, v100 row_ror:2 row_mask:0xf bank_mask:0xf
	s_nop 0
	v_mov_b32_dpp v106, v88 row_shr:1 row_mask:0xf bank_mask:0xf
	v_fma_f32 v100, v89, v137, v129
	v_mov_b32_dpp v107, v88 row_shr:2 row_mask:0xf bank_mask:0xf
	v_fma_f32 v88, v88, v136, v128
	v_pk_mul_f32 v[106:107], v[94:95], v[106:107]
	s_nop 0
	v_add_f32_e32 v88, v88, v106
	v_add_f32_e32 v108, v88, v107
	v_mov_b32_e32 v106, v189
	v_mov_b32_e32 v107, v189
	s_nop 0
	v_mov_b32_dpp v106, v101 row_ror:1 row_mask:0xf bank_mask:0xf
	v_mov_b32_dpp v107, v101 row_ror:2 row_mask:0xf bank_mask:0xf
	v_mov_b32_e32 v101, v134
	v_mov_b32_dpp v106, v89 row_shr:1 row_mask:0xf bank_mask:0xf
	v_mov_b32_dpp v107, v89 row_shr:2 row_mask:0xf bank_mask:0xf
	v_pk_mul_f32 v[88:89], v[132:133], v[106:107]
	v_mov_b32_e32 v134, v155
	v_add_f32_e32 v88, v100, v88
	v_add_f32_e32 v106, v88, v89
	v_mov_b32_e32 v88, v189
	v_mov_b32_e32 v89, v189
	v_mov_b32_e32 v100, v154
	v_mov_b32_dpp v88, v102 row_ror:1 row_mask:0xf bank_mask:0xf
	v_mov_b32_dpp v89, v102 row_ror:2 row_mask:0xf bank_mask:0xf
	s_nop 0
	v_mov_b32_dpp v88, v90 row_shr:1 row_mask:0xf bank_mask:0xf
	v_mov_b32_dpp v89, v90 row_shr:2 row_mask:0xf bank_mask:0xf
	v_fma_f32 v90, v90, v138, v130
	v_pk_mul_f32 v[88:89], v[100:101], v[88:89]
	s_nop 0
	v_add_f32_e32 v88, v90, v88
	v_add_f32_e32 v90, v88, v89
	v_mov_b32_e32 v88, v189
	v_mov_b32_e32 v89, v189
	s_nop 0
	v_mov_b32_dpp v88, v103 row_ror:1 row_mask:0xf bank_mask:0xf
	v_mov_b32_dpp v89, v103 row_ror:2 row_mask:0xf bank_mask:0xf
	s_nop 0
	v_mov_b32_dpp v88, v91 row_shr:1 row_mask:0xf bank_mask:0xf
	v_mov_b32_dpp v89, v91 row_shr:2 row_mask:0xf bank_mask:0xf
	v_fma_f32 v91, v91, v139, v131
	v_pk_mul_f32 v[88:89], v[134:135], v[88:89]
	s_nop 0
	v_add_f32_e32 v88, v91, v88
	v_add_f32_e32 v88, v88, v89
	v_mul_f32_e32 v102, 0xbfb8aa3b, v111
	v_exp_f32_e32 v102, v102
	v_mul_f32_e32 v89, 0xbfb8aa3b, v109
	v_exp_f32_e32 v89, v89
	v_mul_f32_e32 v91, 0xbfb8aa3b, v110
	v_add_f32_e32 v102, 1.0, v102
	v_rcp_f32_e32 v102, v102
	v_exp_f32_e32 v91, v91
	v_add_f32_e32 v89, 1.0, v89
	v_rcp_f32_e32 v89, v89
	v_mul_f32_e32 v102, v111, v102
	v_mul_f32_e32 v90, v102, v90
	v_mul_f32_e32 v102, 0xbfb8aa3b, v114
	v_exp_f32_e32 v102, v102
	v_add_f32_e32 v91, 1.0, v91
	v_rcp_f32_e32 v91, v91
	v_mul_f32_e32 v89, v109, v89
	v_add_f32_e32 v102, 1.0, v102
	v_rcp_f32_e32 v102, v102
	v_mul_f32_e32 v89, v89, v108
	v_mul_f32_e32 v91, v110, v91
	v_mul_f32_e32 v91, v91, v106
	v_mul_f32_e32 v102, v114, v102
	v_mul_f32_e32 v102, v102, v88
	v_cvt_pk_bf16_f32 v88, v89, v91
	v_cvt_pk_bf16_f32 v89, v90, v102
	s_add_i32 s0, s19, 0xffff8090
	s_lshr_b32 s0, s0, 3
	s_and_b32 s0, s0, 0x7ffffe
	v_or_b32_e32 v154, s0, v215
	v_mad_u32_u24 v102, v154, s1, v188
	v_add_u32_e32 v90, s3, v102
	v_mov_b32_e32 v91, v189
	v_lshl_add_u64 v[90:91], v[90:91], 2, s[6:7]
	global_load_dwordx4 v[106:109], v[90:91], off
	v_mov_b32_e32 v90, v189
	v_mov_b32_e32 v91, v189
	s_waitcnt vmcnt(0)
	v_mov_b32_dpp v90, v106 row_ror:1 row_mask:0xf bank_mask:0xf
	v_mov_b32_dpp v91, v106 row_ror:2 row_mask:0xf bank_mask:0xf
	s_nop 0
	v_mov_b32_dpp v90, v84 row_shr:1 row_mask:0xf bank_mask:0xf
	v_fma_f32 v106, v85, v149, v141
	v_mov_b32_dpp v91, v84 row_shr:2 row_mask:0xf bank_mask:0xf
	v_fma_f32 v84, v84, v148, v140
	v_pk_mul_f32 v[90:91], v[98:99], v[90:91]
	s_nop 0
	v_add_f32_e32 v84, v84, v90
	v_add_f32_e32 v103, v84, v91
	v_mov_b32_e32 v90, v189
	v_mov_b32_e32 v91, v189
	s_nop 0
	v_mov_b32_dpp v90, v107 row_ror:1 row_mask:0xf bank_mask:0xf
	v_mov_b32_dpp v91, v107 row_ror:2 row_mask:0xf bank_mask:0xf
	s_nop 0
	v_mov_b32_dpp v90, v85 row_shr:1 row_mask:0xf bank_mask:0xf
	v_mov_b32_dpp v91, v85 row_shr:2 row_mask:0xf bank_mask:0xf
	v_pk_mul_f32 v[84:85], v[144:145], v[90:91]
	s_nop 0
	v_add_f32_e32 v84, v106, v84
	v_add_f32_e32 v106, v84, v85
	v_mov_b32_e32 v84, v189
	v_mov_b32_e32 v85, v189
	s_nop 0
	v_mov_b32_dpp v84, v108 row_ror:1 row_mask:0xf bank_mask:0xf
	v_mov_b32_dpp v85, v108 row_ror:2 row_mask:0xf bank_mask:0xf
	s_nop 0
	v_mov_b32_dpp v84, v86 row_shr:1 row_mask:0xf bank_mask:0xf
	v_mov_b32_dpp v85, v86 row_shr:2 row_mask:0xf bank_mask:0xf
	v_fma_f32 v86, v86, v150, v142
	v_pk_mul_f32 v[84:85], v[92:93], v[84:85]
	s_nop 0
	v_add_f32_e32 v84, v86, v84
	v_add_f32_e32 v107, v84, v85
	v_mov_b32_e32 v84, v189
	v_mov_b32_e32 v85, v189
	v_fma_f32 v86, v87, v151, v143
	v_mov_b32_dpp v84, v109 row_ror:1 row_mask:0xf bank_mask:0xf
	v_mov_b32_dpp v85, v109 row_ror:2 row_mask:0xf bank_mask:0xf
	s_nop 0
	v_mov_b32_dpp v84, v87 row_shr:1 row_mask:0xf bank_mask:0xf
	v_mov_b32_dpp v85, v87 row_shr:2 row_mask:0xf bank_mask:0xf
	v_pk_mul_f32 v[84:85], v[146:147], v[84:85]
	s_nop 0
	v_add_f32_e32 v84, v86, v84
	v_add_f32_e32 v108, v84, v85
	v_add_u32_e32 v84, s2, v102
	v_mov_b32_e32 v85, v189
	v_lshl_add_u64 v[84:85], v[84:85], 2, s[6:7]
	global_load_dwordx4 v[84:87], v[84:85], off
	v_mov_b32_e32 v90, v189
	v_mov_b32_e32 v91, v189
	s_waitcnt vmcnt(0)
;     template <bool SAMP, bool BND>
;     __device__ __forceinline__ void conv_act(const f32x4 (&acc)[2][2][4][2], const Unit& u, int wr, int fr, int rbase, int ccol, LAS float* halo, const LAS float* wl_) const {
;     ...
;             for (int ai = 0; ai < 2; ++ai)
; #pragma unroll
;                 for (int m = 0; m < 4; ++m) {
;                     const int row = rbase + 128 * ai + 16 * m + fr;
;                     const bool ok = SAMP || (row < NP && !(ai == 0 && m == 0 && wr == 0 && fr < 2));
;                     const int t4 = (row + 2) & 2047;
;                     const float z1 = (BND && t4 == 2) ? 0.f : 1.f, z2 = (BND && (t4 == 2 || t4 == 3)) ? 0.f : 1.f;
;                     f32x4 a[2];
; #pragma unroll
;                     for (int bj = 0; bj < 2; ++bj) {
;                         f32x4 prev;
;                         if (SAMP) { const int s = (rbase + 128 * ai + 16 * m - NP) >> 4; prev = *(const f32x4*)(sffn + (unsigned)((s * 2 + (fr & 1)) * UPW + bj * DFF + u.pn * 128 + ccol + 4 * n)); }
;                         else if (m > 0) prev = acc[ai][bj][m > 0 ? m - 1 : 0][n];
;                         else { const int blk = 2 * ai + wr; prev = (f32x4){0.f, 0.f, 0.f, 0.f}; if (blk > 0) prev = *(const LAS f32x4*)(halo + ((blk - 1) * 2 + (fr & 1)) * 256 + bj * 128 + ccol + 4 * n); }
;                         const f32x4 cur = acc[ai][bj][m][n];
; #pragma unroll
;                         for (int j = 0; j < 4; ++j) {
;                             const float p1 = dppf<0x111>(dppf<0x121>(0.f, prev[j]), cur[j]);
;                             const float p2 = dppf<0x112>(dppf<0x122>(0.f, prev[j]), cur[j]);
;                             a[bj][j] = BB[bj][j] + W2[bj][j] * cur[j] + W1[bj][j] * (BND ? p1 * z1 : p1) + W0[bj][j] * (BND ? p2 * z2 : p2);
;                         }
;                         if (BND) { if (ok && t4 < 2 && row >= 2046) *(f32x4*)(offp + (unsigned)(((((row + 2) >> 11) - 1) * 2 + t4) * UPW + bj * DFF + u.pn * 128 + ccol + 4 * n)) = cur; }
;                         __builtin_amdgcn_sched_barrier(0);
;                     }
;                     float o[4];
; #pragma unroll
;                     for (int j = 0; j < 4; ++j) { const float g = a[0][j], v = a[1][j]; o[j] = g * __builtin_amdgcn_rcpf(1.0f + __builtin_amdgcn_exp2f(-g * LOG2E)) * v; }
;                     u32x2 w; w.x = cvt_pk_bf16(o[0], o[1]); w.y = cvt_pk_bf16(o[2], o[3]);
	v_mov_b32_dpp v90, v84 row_ror:1 row_mask:0xf bank_mask:0xf
	v_mov_b32_dpp v91, v84 row_ror:2 row_mask:0xf bank_mask:0xf
	s_nop 0
	v_mov_b32_dpp v90, v80 row_shr:1 row_mask:0xf bank_mask:0xf
	v_mov_b32_dpp v91, v80 row_shr:2 row_mask:0xf bank_mask:0xf
	v_fma_f32 v80, v80, v136, v128
	v_pk_mul_f32 v[90:91], v[94:95], v[90:91]
	s_nop 0
	v_add_f32_e32 v80, v80, v90
	v_add_f32_e32 v84, v80, v91
	v_mov_b32_e32 v90, v189
	v_mov_b32_e32 v91, v189
	s_nop 0
	v_mov_b32_dpp v90, v85 row_ror:1 row_mask:0xf bank_mask:0xf
	v_mov_b32_dpp v91, v85 row_ror:2 row_mask:0xf bank_mask:0xf
	v_fma_f32 v85, v81, v137, v129
	v_mov_b32_dpp v90, v81 row_shr:1 row_mask:0xf bank_mask:0xf
	v_mov_b32_dpp v91, v81 row_shr:2 row_mask:0xf bank_mask:0xf
	v_pk_mul_f32 v[80:81], v[132:133], v[90:91]
	s_nop 0
	v_add_f32_e32 v80, v85, v80
	v_add_f32_e32 v85, v80, v81
	v_mov_b32_e32 v80, v189
	v_mov_b32_e32 v81, v189
	s_nop 0
	v_mov_b32_dpp v80, v86 row_ror:1 row_mask:0xf bank_mask:0xf
	v_mov_b32_dpp v81, v86 row_ror:2 row_mask:0xf bank_mask:0xf
	s_nop 0
	v_mov_b32_dpp v80, v82 row_shr:1 row_mask:0xf bank_mask:0xf
	v_mov_b32_dpp v81, v82 row_shr:2 row_mask:0xf bank_mask:0xf
	v_fma_f32 v82, v82, v138, v130
	v_pk_mul_f32 v[80:81], v[100:101], v[80:81]
	s_nop 0
	v_add_f32_e32 v80, v82, v80
	v_add_f32_e32 v82, v80, v81
	v_mov_b32_e32 v80, v189
	v_mov_b32_e32 v81, v189
	s_nop 0
	v_mov_b32_dpp v80, v87 row_ror:1 row_mask:0xf bank_mask:0xf
	v_mov_b32_dpp v81, v87 row_ror:2 row_mask:0xf bank_mask:0xf
	s_nop 0
	v_mov_b32_dpp v80, v83 row_shr:1 row_mask:0xf bank_mask:0xf
	v_mov_b32_dpp v81, v83 row_shr:2 row_mask:0xf bank_mask:0xf
	v_fma_f32 v83, v83, v139, v131
	v_pk_mul_f32 v[80:81], v[134:135], v[80:81]
	s_nop 0
	v_add_f32_e32 v80, v83, v80
	v_add_f32_e32 v80, v80, v81
	v_mul_f32_e32 v81, 0xbfb8aa3b, v103
	v_exp_f32_e32 v81, v81
	v_mul_f32_e32 v83, 0xbfb8aa3b, v106
	v_exp_f32_e32 v83, v83
	v_add_f32_e32 v81, 1.0, v81
	v_rcp_f32_e32 v81, v81
	v_add_f32_e32 v83, 1.0, v83
	v_rcp_f32_e32 v83, v83
	v_mul_f32_e32 v81, v103, v81
	v_mul_f32_e32 v81, v81, v84
	v_mul_f32_e32 v84, 0xbfb8aa3b, v107
	v_exp_f32_e32 v84, v84
	v_mul_f32_e32 v83, v106, v83
	v_mul_f32_e32 v83, v83, v85
	v_add_f32_e32 v84, 1.0, v84
	v_rcp_f32_e32 v84, v84
	s_nop 0
	v_mul_f32_e32 v84, v107, v84
	v_mul_f32_e32 v82, v84, v82
	v_mul_f32_e32 v84, 0xbfb8aa3b, v108
	v_exp_f32_e32 v84, v84
	s_nop 0
	v_add_f32_e32 v84, 1.0, v84
	v_rcp_f32_e32 v84, v84
	s_nop 0
	v_mul_f32_e32 v84, v108, v84
	v_mul_f32_e32 v84, v84, v80
	v_cvt_pk_bf16_f32 v80, v81, v83
	v_cvt_pk_bf16_f32 v81, v82, v84
	s_add_i32 s0, s19, 0xffff80a0
	s_lshr_b32 s0, s0, 3
	s_and_b32 s0, s0, 0x7ffffe
	v_or_b32_e32 v153, s0, v215
	v_mad_u32_u24 v90, v153, s1, v188
	v_add_u32_e32 v82, s3, v90
	v_mov_b32_e32 v83, v189
	v_lshl_add_u64 v[82:83], v[82:83], 2, s[6:7]
	global_load_dwordx4 v[82:85], v[82:83], off
	v_mov_b32_e32 v86, v189
	v_mov_b32_e32 v87, v189
	s_waitcnt vmcnt(0)
	v_mov_b32_dpp v86, v82 row_ror:1 row_mask:0xf bank_mask:0xf
	v_mov_b32_dpp v87, v82 row_ror:2 row_mask:0xf bank_mask:0xf
	s_nop 0
	v_mov_b32_dpp v86, v76 row_shr:1 row_mask:0xf bank_mask:0xf
	v_fma_f32 v82, v77, v149, v141
	v_mov_b32_dpp v87, v76 row_shr:2 row_mask:0xf bank_mask:0xf
	v_fma_f32 v76, v76, v148, v140
	v_pk_mul_f32 v[86:87], v[98:99], v[86:87]
	s_nop 0
	v_add_f32_e32 v76, v76, v86
	v_add_f32_e32 v91, v76, v87
	v_mov_b32_e32 v86, v189
	v_mov_b32_e32 v87, v189
	s_nop 0
	v_mov_b32_dpp v86, v83 row_ror:1 row_mask:0xf bank_mask:0xf
	v_mov_b32_dpp v87, v83 row_ror:2 row_mask:0xf bank_mask:0xf
	s_nop 0
	v_mov_b32_dpp v86, v77 row_shr:1 row_mask:0xf bank_mask:0xf
	v_mov_b32_dpp v87, v77 row_shr:2 row_mask:0xf bank_mask:0xf
	v_pk_mul_f32 v[76:77], v[144:145], v[86:87]
	s_nop 0
	v_add_f32_e32 v76, v82, v76
	v_add_f32_e32 v86, v76, v77
	v_mov_b32_e32 v76, v189
	v_mov_b32_e32 v77, v189
	s_nop 0
	v_mov_b32_dpp v76, v84 row_ror:1 row_mask:0xf bank_mask:0xf
	v_mov_b32_dpp v77, v84 row_ror:2 row_mask:0xf bank_mask:0xf
	s_nop 0
	v_mov_b32_dpp v76, v78 row_shr:1 row_mask:0xf bank_mask:0xf
	v_mov_b32_dpp v77, v78 row_shr:2 row_mask:0xf bank_mask:0xf
	v_fma_f32 v78, v78, v150, v142
	v_pk_mul_f32 v[76:77], v[92:93], v[76:77]
	s_nop 0
	v_add_f32_e32 v76, v78, v76
	v_add_f32_e32 v84, v76, v77
	v_mov_b32_e32 v76, v189
	v_mov_b32_e32 v77, v189
	v_fma_f32 v78, v79, v151, v143
	v_mov_b32_dpp v76, v85 row_ror:1 row_mask:0xf bank_mask:0xf
	v_mov_b32_dpp v77, v85 row_ror:2 row_mask:0xf bank_mask:0xf
	s_nop 0
	v_mov_b32_dpp v76, v79 row_shr:1 row_mask:0xf bank_mask:0xf
	v_mov_b32_dpp v77, v79 row_shr:2 row_mask:0xf bank_mask:0xf
	v_pk_mul_f32 v[76:77], v[146:147], v[76:77]
	s_nop 0
	v_add_f32_e32 v76, v78, v76
	v_add_f32_e32 v85, v76, v77
	v_add_u32_e32 v76, s2, v90
	v_mov_b32_e32 v77, v189
	v_lshl_add_u64 v[76:77], v[76:77], 2, s[6:7]
	global_load_dwordx4 v[76:79], v[76:77], off
	v_mov_b32_e32 v82, v189
	v_mov_b32_e32 v83, v189
	s_waitcnt vmcnt(0)
;     template <bool SAMP, bool BND>
;     __device__ __forceinline__ void conv_act(const f32x4 (&acc)[2][2][4][2], const Unit& u, int wr, int fr, int rbase, int ccol, LAS float* halo, const LAS float* wl_) const {
;     ...
;             for (int ai = 0; ai < 2; ++ai)
; #pragma unroll
;                 for (int m = 0; m < 4; ++m) {
;                     const int row = rbase + 128 * ai + 16 * m + fr;
;                     const bool ok = SAMP || (row < NP && !(ai == 0 && m == 0 && wr == 0 && fr < 2));
;                     const int t4 = (row + 2) & 2047;
;                     const float z1 = (BND && t4 == 2) ? 0.f : 1.f, z2 = (BND && (t4 == 2 || t4 == 3)) ? 0.f : 1.f;
;                     f32x4 a[2];
; #pragma unroll
;                     for (int bj = 0; bj < 2; ++bj) {
;                         f32x4 prev;
;                         if (SAMP) { const int s = (rbase + 128 * ai + 16 * m - NP) >> 4; prev = *(const f32x4*)(sffn + (unsigned)((s * 2 + (fr & 1)) * UPW + bj * DFF + u.pn * 128 + ccol + 4 * n)); }
;                         else if (m > 0) prev = acc[ai][bj][m > 0 ? m - 1 : 0][n];
;                         else { const int blk = 2 * ai + wr; prev = (f32x4){0.f, 0.f, 0.f, 0.f}; if (blk > 0) prev = *(const LAS f32x4*)(halo + ((blk - 1) * 2 + (fr & 1)) * 256 + bj * 128 + ccol + 4 * n); }
;                         const f32x4 cur = acc[ai][bj][m][n];
; #pragma unroll
;                         for (int j = 0; j < 4; ++j) {
;                             const float p1 = dppf<0x111>(dppf<0x121>(0.f, prev[j]), cur[j]);
;                             const float p2 = dppf<0x112>(dppf<0x122>(0.f, prev[j]), cur[j]);
;                             a[bj][j] = BB[bj][j] + W2[bj][j] * cur[j] + W1[bj][j] * (BND ? p1 * z1 : p1) + W0[bj][j] * (BND ? p2 * z2 : p2);
;                         }
;                         if (BND) { if (ok && t4 < 2 && row >= 2046) *(f32x4*)(offp + (unsigned)(((((row + 2) >> 11) - 1) * 2 + t4) * UPW + bj * DFF + u.pn * 128 + ccol + 4 * n)) = cur; }
;                         __builtin_amdgcn_sched_barrier(0);
;                     }
;                     float o[4];
; #pragma unroll
;                     for (int j = 0; j < 4; ++j) { const float g = a[0][j], v = a[1][j]; o[j] = g * __builtin_amdgcn_rcpf(1.0f + __builtin_amdgcn_exp2f(-g * LOG2E)) * v; }
;                     u32x2 w; w.x = cvt_pk_bf16(o[0], o[1]); w.y = cvt_pk_bf16(o[2], o[3]);
	v_mov_b32_dpp v82, v76 row_ror:1 row_mask:0xf bank_mask:0xf
	v_mov_b32_dpp v83, v76 row_ror:2 row_mask:0xf bank_mask:0xf
	s_nop 0
	v_mov_b32_dpp v82, v72 row_shr:1 row_mask:0xf bank_mask:0xf
	v_mov_b32_dpp v83, v72 row_shr:2 row_mask:0xf bank_mask:0xf
	v_fma_f32 v72, v72, v136, v128
	v_pk_mul_f32 v[82:83], v[94:95], v[82:83]
	s_nop 0
	v_add_f32_e32 v72, v72, v82
	v_add_f32_e32 v76, v72, v83
	v_mov_b32_e32 v82, v189
	v_mov_b32_e32 v83, v189
	s_nop 0
	v_mov_b32_dpp v82, v77 row_ror:1 row_mask:0xf bank_mask:0xf
	v_mov_b32_dpp v83, v77 row_ror:2 row_mask:0xf bank_mask:0xf
	v_fma_f32 v77, v73, v137, v129
	v_mov_b32_dpp v82, v73 row_shr:1 row_mask:0xf bank_mask:0xf
	v_mov_b32_dpp v83, v73 row_shr:2 row_mask:0xf bank_mask:0xf
	v_pk_mul_f32 v[72:73], v[132:133], v[82:83]
	s_nop 0
	v_add_f32_e32 v72, v77, v72
	v_add_f32_e32 v77, v72, v73
	v_mov_b32_e32 v72, v189
	v_mov_b32_e32 v73, v189
	s_nop 0
	v_mov_b32_dpp v72, v78 row_ror:1 row_mask:0xf bank_mask:0xf
	v_mov_b32_dpp v73, v78 row_ror:2 row_mask:0xf bank_mask:0xf
	s_nop 0
	v_mov_b32_dpp v72, v74 row_shr:1 row_mask:0xf bank_mask:0xf
	v_mov_b32_dpp v73, v74 row_shr:2 row_mask:0xf bank_mask:0xf
	v_fma_f32 v74, v74, v138, v130
	v_pk_mul_f32 v[72:73], v[100:101], v[72:73]
	s_nop 0
	v_add_f32_e32 v72, v74, v72
	v_add_f32_e32 v74, v72, v73
	v_mov_b32_e32 v72, v189
	v_mov_b32_e32 v73, v189
	s_nop 0
	v_mov_b32_dpp v72, v79 row_ror:1 row_mask:0xf bank_mask:0xf
	v_mov_b32_dpp v73, v79 row_ror:2 row_mask:0xf bank_mask:0xf
	s_nop 0
	v_mov_b32_dpp v72, v75 row_shr:1 row_mask:0xf bank_mask:0xf
	v_mov_b32_dpp v73, v75 row_shr:2 row_mask:0xf bank_mask:0xf
	v_fma_f32 v75, v75, v139, v131
	v_pk_mul_f32 v[72:73], v[134:135], v[72:73]
	s_nop 0
	v_add_f32_e32 v72, v75, v72
	v_add_f32_e32 v72, v72, v73
	v_mul_f32_e32 v73, 0xbfb8aa3b, v91
	v_exp_f32_e32 v73, v73
	v_mul_f32_e32 v75, 0xbfb8aa3b, v86
	v_exp_f32_e32 v75, v75
	v_add_f32_e32 v73, 1.0, v73
	v_rcp_f32_e32 v73, v73
	v_add_f32_e32 v75, 1.0, v75
	v_rcp_f32_e32 v75, v75
	v_mul_f32_e32 v73, v91, v73
	v_mul_f32_e32 v73, v73, v76
	v_mul_f32_e32 v76, 0xbfb8aa3b, v84
	v_exp_f32_e32 v76, v76
	v_mul_f32_e32 v75, v86, v75
	v_mul_f32_e32 v75, v75, v77
	v_add_f32_e32 v76, 1.0, v76
	v_rcp_f32_e32 v76, v76
	s_nop 0
	v_mul_f32_e32 v76, v84, v76
	v_mul_f32_e32 v74, v76, v74
	v_mul_f32_e32 v76, 0xbfb8aa3b, v85
	v_exp_f32_e32 v76, v76
	s_nop 0
	v_add_f32_e32 v76, 1.0, v76
	v_rcp_f32_e32 v76, v76
	s_nop 0
	v_mul_f32_e32 v76, v85, v76
	v_mul_f32_e32 v76, v76, v72
	v_cvt_pk_bf16_f32 v72, v73, v75
	v_cvt_pk_bf16_f32 v73, v74, v76
	s_addk_i32 s19, 0x80b0
	s_lshr_b32 s0, s19, 3
	s_and_b32 s0, s0, 0x7ffffe
	v_or_b32_e32 v152, s0, v215
	v_mad_u32_u24 v82, v152, s1, v188
	v_add_u32_e32 v74, s3, v82
	v_mov_b32_e32 v75, v189
	v_lshl_add_u64 v[74:75], v[74:75], 2, s[6:7]
	global_load_dwordx4 v[74:77], v[74:75], off
	v_mov_b32_e32 v78, v189
	v_mov_b32_e32 v79, v189
	v_fmac_f32_e32 v143, v71, v151
	s_waitcnt vmcnt(0)
	v_mov_b32_dpp v78, v74 row_ror:1 row_mask:0xf bank_mask:0xf
	v_mov_b32_dpp v79, v74 row_ror:2 row_mask:0xf bank_mask:0xf
	s_nop 0
	v_mov_b32_dpp v78, v68 row_shr:1 row_mask:0xf bank_mask:0xf
	v_fma_f32 v74, v69, v149, v141
	v_mov_b32_dpp v79, v68 row_shr:2 row_mask:0xf bank_mask:0xf
	v_fma_f32 v68, v68, v148, v140
	v_pk_mul_f32 v[78:79], v[98:99], v[78:79]
	s_nop 0
	v_add_f32_e32 v68, v68, v78
	v_add_f32_e32 v83, v68, v79
	v_mov_b32_e32 v78, v189
	v_mov_b32_e32 v79, v189
	s_nop 0
	v_mov_b32_dpp v78, v75 row_ror:1 row_mask:0xf bank_mask:0xf
	v_mov_b32_dpp v79, v75 row_ror:2 row_mask:0xf bank_mask:0xf
	s_nop 0
	v_mov_b32_dpp v78, v69 row_shr:1 row_mask:0xf bank_mask:0xf
	v_mov_b32_dpp v79, v69 row_shr:2 row_mask:0xf bank_mask:0xf
	v_pk_mul_f32 v[68:69], v[144:145], v[78:79]
	s_nop 0
	v_add_f32_e32 v68, v74, v68
	v_add_f32_e32 v78, v68, v69
	v_mov_b32_e32 v68, v189
	v_mov_b32_e32 v69, v189
	s_nop 0
	v_mov_b32_dpp v68, v76 row_ror:1 row_mask:0xf bank_mask:0xf
	v_mov_b32_dpp v69, v76 row_ror:2 row_mask:0xf bank_mask:0xf
	s_nop 0
	v_mov_b32_dpp v68, v70 row_shr:1 row_mask:0xf bank_mask:0xf
	v_mov_b32_dpp v69, v70 row_shr:2 row_mask:0xf bank_mask:0xf
	v_fma_f32 v70, v70, v150, v142
	v_pk_mul_f32 v[68:69], v[92:93], v[68:69]
	s_nop 0
	v_add_f32_e32 v68, v70, v68
	v_add_f32_e32 v76, v68, v69
	v_mov_b32_e32 v68, v189
	v_mov_b32_e32 v69, v189
	s_nop 0
	v_mov_b32_dpp v68, v77 row_ror:1 row_mask:0xf bank_mask:0xf
	v_mov_b32_dpp v69, v77 row_ror:2 row_mask:0xf bank_mask:0xf
	s_nop 0
	v_mov_b32_dpp v68, v71 row_shr:1 row_mask:0xf bank_mask:0xf
	v_mov_b32_dpp v69, v71 row_shr:2 row_mask:0xf bank_mask:0xf
	v_pk_mul_f32 v[68:69], v[146:147], v[68:69]
	s_nop 0
	v_add_f32_e32 v68, v143, v68
	v_add_f32_e32 v77, v68, v69
	v_add_u32_e32 v68, s2, v82
	v_mov_b32_e32 v69, v189
	v_lshl_add_u64 v[68:69], v[68:69], 2, s[6:7]
	global_load_dwordx4 v[68:71], v[68:69], off
	v_mov_b32_e32 v74, v189
	v_mov_b32_e32 v75, v189
	v_fmac_f32_e32 v131, v67, v139
	s_waitcnt vmcnt(0)
; #define LAS __attribute__((address_space(3)))
;     template <bool SAMP, bool BND>
;     __device__ __forceinline__ void conv_act(const f32x4 (&acc)[2][2][4][2], const Unit& u, int wr, int fr, int rbase, int ccol, LAS float* halo, const LAS float* wl_) const {
;     ...
;         for (int n = 0; n < 2; ++n) {
;             f32x4 W0[2], W1[2], W2[2], BB[2];
; #pragma unroll
;             for (int bj = 0; bj < 2; ++bj) {
;                 const int tc = bj * 128 + ccol + 4 * n;
;                 W0[bj] = *(const LAS f32x4*)(wl_ + tc); W1[bj] = *(const LAS f32x4*)(wl_ + 256 + tc); W2[bj] = *(const LAS f32x4*)(wl_ + 512 + tc); BB[bj] = *(const LAS f32x4*)(wl_ + 768 + tc);
;             }
; #pragma unroll
;             for (int ai = 0; ai < 2; ++ai)
; #pragma unroll
;                 for (int m = 0; m < 4; ++m) {
;                     const int row = rbase + 128 * ai + 16 * m + fr;
;                     const bool ok = SAMP || (row < NP && !(ai == 0 && m == 0 && wr == 0 && fr < 2));
;                     const int t4 = (row + 2) & 2047;
;                     const float z1 = (BND && t4 == 2) ? 0.f : 1.f, z2 = (BND && (t4 == 2 || t4 == 3)) ? 0.f : 1.f;
;                     f32x4 a[2];
; #pragma unroll
;                     for (int bj = 0; bj < 2; ++bj) {
;                         f32x4 prev;
;                         if (SAMP) { const int s = (rbase + 128 * ai + 16 * m - NP) >> 4; prev = *(const f32x4*)(sffn + (unsigned)((s * 2 + (fr & 1)) * UPW + bj * DFF + u.pn * 128 + ccol + 4 * n)); }
;                         else if (m > 0) prev = acc[ai][bj][m > 0 ? m - 1 : 0][n];
;                         else { const int blk = 2 * ai + wr; prev = (f32x4){0.f, 0.f, 0.f, 0.f}; if (blk > 0) prev = *(const LAS f32x4*)(halo + ((blk - 1) * 2 + (fr & 1)) * 256 + bj * 128 + ccol + 4 * n); }
;                         const f32x4 cur = acc[ai][bj][m][n];
; #pragma unroll
;                         for (int j = 0; j < 4; ++j) {
;                             const float p1 = dppf<0x111>(dppf<0x121>(0.f, prev[j]), cur[j]);
;                             const float p2 = dppf<0x112>(dppf<0x122>(0.f, prev[j]), cur[j]);
;                             a[bj][j] = BB[bj][j] + W2[bj][j] * cur[j] + W1[bj][j] * (BND ? p1 * z1 : p1) + W0[bj][j] * (BND ? p2 * z2 : p2);
;                         }
	v_mov_b32_dpp v74, v68 row_ror:1 row_mask:0xf bank_mask:0xf
	v_mov_b32_dpp v75, v68 row_ror:2 row_mask:0xf bank_mask:0xf
	s_nop 0
	v_mov_b32_dpp v74, v64 row_shr:1 row_mask:0xf bank_mask:0xf
	v_mov_b32_dpp v75, v64 row_shr:2 row_mask:0xf bank_mask:0xf
	v_fma_f32 v64, v64, v136, v128
	v_pk_mul_f32 v[74:75], v[94:95], v[74:75]
	s_nop 0
	v_add_f32_e32 v64, v64, v74
	v_add_f32_e32 v68, v64, v75
	v_mov_b32_e32 v74, v189
	v_mov_b32_e32 v75, v189
	s_nop 0
	v_mov_b32_dpp v74, v69 row_ror:1 row_mask:0xf bank_mask:0xf
	v_mov_b32_dpp v75, v69 row_ror:2 row_mask:0xf bank_mask:0xf
	v_fma_f32 v69, v65, v137, v129
	v_mov_b32_dpp v74, v65 row_shr:1 row_mask:0xf bank_mask:0xf
	v_mov_b32_dpp v75, v65 row_shr:2 row_mask:0xf bank_mask:0xf
	v_pk_mul_f32 v[64:65], v[132:133], v[74:75]
	s_nop 0
	v_add_f32_e32 v64, v69, v64
	v_add_f32_e32 v69, v64, v65
	v_mov_b32_e32 v64, v189
	v_mov_b32_e32 v65, v189
	s_nop 0
	v_mov_b32_dpp v64, v70 row_ror:1 row_mask:0xf bank_mask:0xf
	v_mov_b32_dpp v65, v70 row_ror:2 row_mask:0xf bank_mask:0xf
	s_nop 0
	v_mov_b32_dpp v64, v66 row_shr:1 row_mask:0xf bank_mask:0xf
	v_mov_b32_dpp v65, v66 row_shr:2 row_mask:0xf bank_mask:0xf
	v_fma_f32 v66, v66, v138, v130
	v_pk_mul_f32 v[64:65], v[100:101], v[64:65]
	s_nop 0
	v_add_f32_e32 v64, v66, v64
	v_add_f32_e32 v66, v64, v65
	v_mov_b32_e32 v64, v189
	v_mov_b32_e32 v65, v189
	s_nop 0
	v_mov_b32_dpp v64, v71 row_ror:1 row_mask:0xf bank_mask:0xf
	v_mov_b32_dpp v65, v71 row_ror:2 row_mask:0xf bank_mask:0xf
	s_nop 0
	v_mov_b32_dpp v64, v67 row_shr:1 row_mask:0xf bank_mask:0xf
	v_mov_b32_dpp v65, v67 row_shr:2 row_mask:0xf bank_mask:0xf
	v_pk_mul_f32 v[64:65], v[134:135], v[64:65]
	s_nop 0
	v_add_f32_e32 v64, v131, v64
	v_add_f32_e32 v64, v64, v65
	v_mul_f32_e32 v65, 0xbfb8aa3b, v83
	v_exp_f32_e32 v65, v65
	v_mul_f32_e32 v67, 0xbfb8aa3b, v78
	v_exp_f32_e32 v67, v67
	v_add_f32_e32 v65, 1.0, v65
	v_rcp_f32_e32 v65, v65
	v_add_f32_e32 v67, 1.0, v67
	v_rcp_f32_e32 v67, v67
	v_mul_f32_e32 v65, v83, v65
	v_mul_f32_e32 v65, v65, v68
	v_mul_f32_e32 v68, 0xbfb8aa3b, v76
	v_exp_f32_e32 v68, v68
	v_mul_f32_e32 v67, v78, v67
	v_mul_f32_e32 v67, v67, v69
	v_add_f32_e32 v68, 1.0, v68
	v_rcp_f32_e32 v68, v68
	s_nop 0
	v_mul_f32_e32 v68, v76, v68
	v_mul_f32_e32 v66, v68, v66
	v_mul_f32_e32 v68, 0xbfb8aa3b, v77
	v_exp_f32_e32 v68, v68
	s_nop 0
	v_add_f32_e32 v68, 1.0, v68
	v_rcp_f32_e32 v68, v68
	s_nop 0
	v_mul_f32_e32 v68, v77, v68
	v_mul_f32_e32 v68, v68, v64
	v_cvt_pk_bf16_f32 v64, v65, v67
	v_cvt_pk_bf16_f32 v65, v66, v68
	v_or_b32_e32 v146, 4, v188
	v_mad_u32_u24 v74, v214, s1, v146
	v_add_u32_e32 v70, s3, v74
	v_mov_b32_e32 v71, v189
	v_lshl_add_u64 v[70:71], v[70:71], 2, s[6:7]
	ds_read_b128 v[100:103], v213 offset:16
	ds_read_b128 v[124:127], v213 offset:1040
	ds_read_b128 v[108:111], v213 offset:2064
	ds_read_b128 v[92:95], v213 offset:3088
	ds_read_b128 v[76:79], v213 offset:528
	ds_read_b128 v[116:119], v213 offset:1552
	ds_read_b128 v[84:87], v213 offset:2576
	ds_read_b128 v[66:69], v213 offset:3600
	global_load_dwordx4 v[128:131], v[70:71], off
	v_mov_b32_e32 v98, v189
	v_mov_b32_e32 v122, v189
	v_mov_b32_e32 v136, v189
	v_mov_b32_e32 v70, v189
	v_mov_b32_e32 v144, v189
	v_mov_b32_e32 v114, v189
	v_mov_b32_e32 v106, v189
	s_waitcnt vmcnt(0)
	v_mov_b32_dpp v98, v128 row_ror:1 row_mask:0xf bank_mask:0xf
	v_mov_b32_dpp v122, v128 row_ror:2 row_mask:0xf bank_mask:0xf
	v_mov_b32_e32 v128, v189
	v_mov_b32_dpp v136, v129 row_ror:2 row_mask:0xf bank_mask:0xf
	v_mov_b32_dpp v70, v130 row_ror:1 row_mask:0xf bank_mask:0xf
	v_mov_b32_dpp v128, v129 row_ror:1 row_mask:0xf bank_mask:0xf
	v_mov_b32_dpp v144, v130 row_ror:2 row_mask:0xf bank_mask:0xf
	v_mov_b32_dpp v114, v131 row_ror:1 row_mask:0xf bank_mask:0xf
	v_mov_b32_dpp v106, v131 row_ror:2 row_mask:0xf bank_mask:0xf
	v_mov_b32_dpp v98, v60 row_shr:1 row_mask:0xf bank_mask:0xf
	v_mov_b32_dpp v122, v60 row_shr:2 row_mask:0xf bank_mask:0xf
	v_mov_b32_dpp v128, v61 row_shr:1 row_mask:0xf bank_mask:0xf
	v_mov_b32_dpp v136, v61 row_shr:2 row_mask:0xf bank_mask:0xf
	v_mov_b32_dpp v70, v62 row_shr:1 row_mask:0xf bank_mask:0xf
	v_mov_b32_dpp v144, v62 row_shr:2 row_mask:0xf bank_mask:0xf
	v_mov_b32_dpp v114, v63 row_shr:1 row_mask:0xf bank_mask:0xf
	v_mov_b32_dpp v106, v63 row_shr:2 row_mask:0xf bank_mask:0xf
	v_add_u32_e32 v74, s2, v74
	v_mov_b32_e32 v75, v189
	v_lshl_add_u64 v[74:75], v[74:75], 2, s[6:7]
	global_load_dwordx4 v[148:151], v[74:75], off
	v_mov_b32_e32 v99, v189
	v_mov_b32_e32 v123, v189
	v_mov_b32_e32 v90, v60
	v_mov_b32_e32 v91, v56
	s_waitcnt lgkmcnt(5)
	v_mov_b32_e32 v74, v108
	s_waitcnt lgkmcnt(1)
	v_mov_b32_e32 v75, v84
	v_mov_b32_e32 v82, v92
	s_waitcnt lgkmcnt(0)
	v_mov_b32_e32 v83, v66
	v_mov_b32_e32 v129, v189
	v_mov_b32_e32 v137, v189
	v_pk_fma_f32 v[130:131], v[90:91], v[74:75], v[82:83]
	v_mov_b32_e32 v90, v124
	v_mov_b32_e32 v91, v116
	v_mov_b32_e32 v132, v109
	v_mov_b32_e32 v133, v85
	v_mov_b32_e32 v134, v93
	v_mov_b32_e32 v135, v67
	v_mov_b32_e32 v138, v125
	v_mov_b32_e32 v139, v117
	v_mov_b32_e32 v71, v189
	v_mov_b32_e32 v142, v101
	v_mov_b32_e32 v143, v77
	v_mov_b32_e32 v145, v189
	v_mov_b32_e32 v60, v62
	v_mov_b32_e32 v140, v102
	v_mov_b32_e32 v141, v78
	v_mov_b32_e32 v115, v189
	v_mov_b32_e32 v107, v189
	s_waitcnt vmcnt(0)
;     template <bool SAMP, bool BND>
;     __device__ __forceinline__ void conv_act(const f32x4 (&acc)[2][2][4][2], const Unit& u, int wr, int fr, int rbase, int ccol, LAS float* halo, const LAS float* wl_) const {
;     ...
;             for (int ai = 0; ai < 2; ++ai)
; #pragma unroll
;                 for (int m = 0; m < 4; ++m) {
;                     const int row = rbase + 128 * ai + 16 * m + fr;
;                     const bool ok = SAMP || (row < NP && !(ai == 0 && m == 0 && wr == 0 && fr < 2));
;                     const int t4 = (row + 2) & 2047;
;                     const float z1 = (BND && t4 == 2) ? 0.f : 1.f, z2 = (BND && (t4 == 2 || t4 == 3)) ? 0.f : 1.f;
;                     f32x4 a[2];
; #pragma unroll
;                     for (int bj = 0; bj < 2; ++bj) {
;                         f32x4 prev;
;                         if (SAMP) { const int s = (rbase + 128 * ai + 16 * m - NP) >> 4; prev = *(const f32x4*)(sffn + (unsigned)((s * 2 + (fr & 1)) * UPW + bj * DFF + u.pn * 128 + ccol + 4 * n)); }
;                         else if (m > 0) prev = acc[ai][bj][m > 0 ? m - 1 : 0][n];
;                         else { const int blk = 2 * ai + wr; prev = (f32x4){0.f, 0.f, 0.f, 0.f}; if (blk > 0) prev = *(const LAS f32x4*)(halo + ((blk - 1) * 2 + (fr & 1)) * 256 + bj * 128 + ccol + 4 * n); }
;                         const f32x4 cur = acc[ai][bj][m][n];
; #pragma unroll
;                         for (int j = 0; j < 4; ++j) {
;                             const float p1 = dppf<0x111>(dppf<0x121>(0.f, prev[j]), cur[j]);
;                             const float p2 = dppf<0x112>(dppf<0x122>(0.f, prev[j]), cur[j]);
;                             a[bj][j] = BB[bj][j] + W2[bj][j] * cur[j] + W1[bj][j] * (BND ? p1 * z1 : p1) + W0[bj][j] * (BND ? p2 * z2 : p2);
;                         }
;                         if (BND) { if (ok && t4 < 2 && row >= 2046) *(f32x4*)(offp + (unsigned)(((((row + 2) >> 11) - 1) * 2 + t4) * UPW + bj * DFF + u.pn * 128 + ccol + 4 * n)) = cur; }
;                         __builtin_amdgcn_sched_barrier(0);
;                     }
;                     float o[4];
; #pragma unroll
;                     for (int j = 0; j < 4; ++j) { const float g = a[0][j], v = a[1][j]; o[j] = g * __builtin_amdgcn_rcpf(1.0f + __builtin_amdgcn_exp2f(-g * LOG2E)) * v; }
;                     u32x2 w; w.x = cvt_pk_bf16(o[0], o[1]); w.y = cvt_pk_bf16(o[2], o[3]);
	v_mov_b32_dpp v99, v148 row_ror:1 row_mask:0xf bank_mask:0xf
	v_mov_b32_dpp v123, v148 row_ror:2 row_mask:0xf bank_mask:0xf
	s_nop 0
	v_mov_b32_dpp v99, v56 row_shr:1 row_mask:0xf bank_mask:0xf
	v_mov_b32_dpp v129, v149 row_ror:1 row_mask:0xf bank_mask:0xf
	v_mov_b32_dpp v123, v56 row_shr:2 row_mask:0xf bank_mask:0xf
	v_mov_b32_dpp v137, v149 row_ror:2 row_mask:0xf bank_mask:0xf
	v_mov_b32_e32 v56, v61
	v_pk_fma_f32 v[130:131], v[90:91], v[98:99], v[130:131]
	v_mov_b32_e32 v98, v100
	v_mov_b32_e32 v99, v76
	v_mov_b32_dpp v129, v57 row_shr:1 row_mask:0xf bank_mask:0xf
	v_mov_b32_dpp v137, v57 row_shr:2 row_mask:0xf bank_mask:0xf
	v_pk_fma_f32 v[56:57], v[56:57], v[132:133], v[134:135]
	v_pk_fma_f32 v[122:123], v[98:99], v[122:123], v[130:131]
	v_pk_fma_f32 v[56:57], v[138:139], v[128:129], v[56:57]
	v_mov_b32_dpp v71, v150 row_ror:1 row_mask:0xf bank_mask:0xf
	v_mov_b32_e32 v61, v58
	v_mov_b32_e32 v128, v110
	v_mov_b32_e32 v129, v86
	v_mov_b32_e32 v130, v94
	v_mov_b32_e32 v131, v68
	v_pk_fma_f32 v[56:57], v[142:143], v[136:137], v[56:57]
	v_mov_b32_dpp v71, v58 row_shr:1 row_mask:0xf bank_mask:0xf
	v_mov_b32_dpp v145, v150 row_ror:2 row_mask:0xf bank_mask:0xf
	v_pk_fma_f32 v[60:61], v[60:61], v[128:129], v[130:131]
	v_mov_b32_e32 v136, v126
	v_mov_b32_e32 v137, v118
	v_mov_b32_dpp v145, v58 row_shr:2 row_mask:0xf bank_mask:0xf
	v_pk_fma_f32 v[60:61], v[136:137], v[70:71], v[60:61]
	v_mov_b32_dpp v115, v151 row_ror:1 row_mask:0xf bank_mask:0xf
	v_pk_fma_f32 v[144:145], v[140:141], v[144:145], v[60:61]
	v_mov_b32_dpp v107, v151 row_ror:2 row_mask:0xf bank_mask:0xf
	v_mov_b32_e32 v58, v63
	v_mov_b32_e32 v60, v111
	v_mov_b32_e32 v61, v87
	v_mov_b32_e32 v70, v95
	v_mov_b32_e32 v71, v69
	v_mov_b32_dpp v115, v59 row_shr:1 row_mask:0xf bank_mask:0xf
	v_mov_b32_dpp v107, v59 row_shr:2 row_mask:0xf bank_mask:0xf
	v_pk_fma_f32 v[62:63], v[58:59], v[60:61], v[70:71]
	v_mov_b32_e32 v58, v127
	v_mov_b32_e32 v59, v119
	v_pk_fma_f32 v[114:115], v[58:59], v[114:115], v[62:63]
	v_mov_b32_e32 v62, v103
	v_mov_b32_e32 v63, v79
	v_pk_fma_f32 v[106:107], v[62:63], v[106:107], v[114:115]
	v_mul_f32_e32 v115, 0xbfb8aa3b, v56
	v_exp_f32_e32 v115, v115
	v_mul_f32_e32 v114, 0xbfb8aa3b, v122
	v_exp_f32_e32 v114, v114
	s_movk_i32 s0, 0xb00
	v_add_f32_e32 v115, 1.0, v115
	v_rcp_f32_e32 v115, v115
	v_add_f32_e32 v114, 1.0, v114
	v_rcp_f32_e32 v114, v114
	v_mul_f32_e32 v56, v56, v115
	v_mul_f32_e32 v56, v56, v57
	v_mul_f32_e32 v57, 0xbfb8aa3b, v144
	v_exp_f32_e32 v57, v57
	v_mul_f32_e32 v115, 0xbfb8aa3b, v106
	v_exp_f32_e32 v115, v115
	v_mul_f32_e32 v114, v122, v114
	v_add_f32_e32 v57, 1.0, v57
	v_rcp_f32_e32 v57, v57
	v_add_f32_e32 v115, 1.0, v115
	v_rcp_f32_e32 v115, v115
	v_mul_f32_e32 v114, v114, v123
	v_mul_f32_e32 v57, v144, v57
	v_mul_f32_e32 v57, v57, v145
	v_mul_f32_e32 v106, v106, v115
	v_cvt_pk_bf16_f32 v122, v114, v56
	v_mul_lo_u32 v56, v195, s0
	v_mul_f32_e32 v106, v106, v107
	v_cvt_pk_bf16_f32 v123, v57, v106
	v_add3_u32 v56, v188, s3, v56
	v_mov_b32_e32 v57, v189
	v_lshl_add_u64 v[106:107], v[56:57], 1, s[4:5]
	global_store_dwordx4 v[106:107], v[120:123], off
	v_mad_u32_u24 v57, v198, s1, v146
	v_add_u32_e32 v106, s3, v57
	v_mov_b32_e32 v107, v189
	v_lshl_add_u64 v[106:107], v[106:107], 2, s[6:7]
	global_load_dwordx4 v[120:123], v[106:107], off
	v_mov_b32_e32 v144, v189
	v_mov_b32_e32 v148, v189
	v_mov_b32_e32 v150, v189
	v_mov_b32_e32 v156, v189
	v_mov_b32_e32 v158, v189
	v_mov_b32_e32 v162, v189
	v_mov_b32_e32 v106, v189
	v_mov_b32_e32 v114, v189
	s_waitcnt vmcnt(0)
	v_mov_b32_dpp v144, v120 row_ror:1 row_mask:0xf bank_mask:0xf
	v_mov_b32_dpp v148, v120 row_ror:2 row_mask:0xf bank_mask:0xf
	v_mov_b32_dpp v150, v121 row_ror:1 row_mask:0xf bank_mask:0xf
	v_mov_b32_dpp v156, v121 row_ror:2 row_mask:0xf bank_mask:0xf
	v_mov_b32_dpp v158, v122 row_ror:1 row_mask:0xf bank_mask:0xf
	v_mov_b32_dpp v162, v122 row_ror:2 row_mask:0xf bank_mask:0xf
	v_mov_b32_dpp v106, v123 row_ror:1 row_mask:0xf bank_mask:0xf
	v_mov_b32_dpp v114, v123 row_ror:2 row_mask:0xf bank_mask:0xf
	v_mov_b32_dpp v144, v48 row_shr:1 row_mask:0xf bank_mask:0xf
	v_mov_b32_dpp v148, v48 row_shr:2 row_mask:0xf bank_mask:0xf
	v_mov_b32_dpp v150, v49 row_shr:1 row_mask:0xf bank_mask:0xf
	v_mov_b32_dpp v156, v49 row_shr:2 row_mask:0xf bank_mask:0xf
	v_mov_b32_dpp v158, v50 row_shr:1 row_mask:0xf bank_mask:0xf
	v_mov_b32_dpp v162, v50 row_shr:2 row_mask:0xf bank_mask:0xf
	v_mov_b32_dpp v106, v51 row_shr:1 row_mask:0xf bank_mask:0xf
	v_mov_b32_dpp v114, v51 row_shr:2 row_mask:0xf bank_mask:0xf
	v_add_u32_e32 v120, s2, v57
	v_mov_b32_e32 v121, v189
	v_lshl_add_u64 v[120:121], v[120:121], 2, s[6:7]
	global_load_dwordx4 v[120:123], v[120:121], off
	v_mov_b32_e32 v145, v189
	v_mov_b32_e32 v149, v189
	v_mov_b32_e32 v151, v189
	v_mov_b32_e32 v157, v189
	v_mov_b32_e32 v159, v189
	v_mov_b32_e32 v163, v189
	v_mov_b32_e32 v165, v52
	v_mov_b32_e32 v107, v189
	v_mov_b32_e32 v164, v48
	v_mov_b32_e32 v115, v189
	v_pk_fma_f32 v[164:165], v[164:165], v[74:75], v[82:83]
	s_waitcnt vmcnt(0)
;     template <bool SAMP, bool BND>
;     __device__ __forceinline__ void conv_act(const f32x4 (&acc)[2][2][4][2], const Unit& u, int wr, int fr, int rbase, int ccol, LAS float* halo, const LAS float* wl_) const {
;     ...
;             for (int ai = 0; ai < 2; ++ai)
; #pragma unroll
;                 for (int m = 0; m < 4; ++m) {
;                     const int row = rbase + 128 * ai + 16 * m + fr;
;                     const bool ok = SAMP || (row < NP && !(ai == 0 && m == 0 && wr == 0 && fr < 2));
;                     const int t4 = (row + 2) & 2047;
;                     const float z1 = (BND && t4 == 2) ? 0.f : 1.f, z2 = (BND && (t4 == 2 || t4 == 3)) ? 0.f : 1.f;
;                     f32x4 a[2];
; #pragma unroll
;                     for (int bj = 0; bj < 2; ++bj) {
;                         f32x4 prev;
;                         if (SAMP) { const int s = (rbase + 128 * ai + 16 * m - NP) >> 4; prev = *(const f32x4*)(sffn + (unsigned)((s * 2 + (fr & 1)) * UPW + bj * DFF + u.pn * 128 + ccol + 4 * n)); }
;                         else if (m > 0) prev = acc[ai][bj][m > 0 ? m - 1 : 0][n];
;                         else { const int blk = 2 * ai + wr; prev = (f32x4){0.f, 0.f, 0.f, 0.f}; if (blk > 0) prev = *(const LAS f32x4*)(halo + ((blk - 1) * 2 + (fr & 1)) * 256 + bj * 128 + ccol + 4 * n); }
;                         const f32x4 cur = acc[ai][bj][m][n];
; #pragma unroll
;                         for (int j = 0; j < 4; ++j) {
;                             const float p1 = dppf<0x111>(dppf<0x121>(0.f, prev[j]), cur[j]);
;                             const float p2 = dppf<0x112>(dppf<0x122>(0.f, prev[j]), cur[j]);
;                             a[bj][j] = BB[bj][j] + W2[bj][j] * cur[j] + W1[bj][j] * (BND ? p1 * z1 : p1) + W0[bj][j] * (BND ? p2 * z2 : p2);
;                         }
;                         if (BND) { if (ok && t4 < 2 && row >= 2046) *(f32x4*)(offp + (unsigned)(((((row + 2) >> 11) - 1) * 2 + t4) * UPW + bj * DFF + u.pn * 128 + ccol + 4 * n)) = cur; }
;                         __builtin_amdgcn_sched_barrier(0);
;                     }
;                     float o[4];
; #pragma unroll
;                     for (int j = 0; j < 4; ++j) { const float g = a[0][j], v = a[1][j]; o[j] = g * __builtin_amdgcn_rcpf(1.0f + __builtin_amdgcn_exp2f(-g * LOG2E)) * v; }
;                     u32x2 w; w.x = cvt_pk_bf16(o[0], o[1]); w.y = cvt_pk_bf16(o[2], o[3]);
	v_mov_b32_dpp v145, v120 row_ror:1 row_mask:0xf bank_mask:0xf
	v_mov_b32_dpp v149, v120 row_ror:2 row_mask:0xf bank_mask:0xf
	s_nop 0
	v_mov_b32_dpp v145, v52 row_shr:1 row_mask:0xf bank_mask:0xf
	v_mov_b32_dpp v151, v121 row_ror:1 row_mask:0xf bank_mask:0xf
	v_mov_b32_dpp v149, v52 row_shr:2 row_mask:0xf bank_mask:0xf
	v_mov_b32_dpp v157, v121 row_ror:2 row_mask:0xf bank_mask:0xf
	v_mov_b32_e32 v52, v49
	v_mov_b32_dpp v159, v122 row_ror:1 row_mask:0xf bank_mask:0xf
	v_mov_b32_dpp v163, v122 row_ror:2 row_mask:0xf bank_mask:0xf
	v_mov_b32_dpp v151, v53 row_shr:1 row_mask:0xf bank_mask:0xf
	v_mov_b32_dpp v157, v53 row_shr:2 row_mask:0xf bank_mask:0xf
	v_pk_fma_f32 v[48:49], v[52:53], v[132:133], v[134:135]
	v_mov_b32_dpp v159, v54 row_shr:1 row_mask:0xf bank_mask:0xf
	v_mov_b32_dpp v163, v54 row_shr:2 row_mask:0xf bank_mask:0xf
	v_mov_b32_e32 v52, v50
	v_mov_b32_e32 v53, v54
	v_mov_b32_dpp v107, v123 row_ror:1 row_mask:0xf bank_mask:0xf
	v_mov_b32_e32 v54, v51
	v_pk_fma_f32 v[52:53], v[52:53], v[128:129], v[130:131]
	v_mov_b32_dpp v107, v55 row_shr:1 row_mask:0xf bank_mask:0xf
	v_mov_b32_dpp v115, v123 row_ror:2 row_mask:0xf bank_mask:0xf
	v_pk_fma_f32 v[50:51], v[54:55], v[60:61], v[70:71]
	v_pk_fma_f32 v[144:145], v[90:91], v[144:145], v[164:165]
	v_pk_fma_f32 v[48:49], v[138:139], v[150:151], v[48:49]
	v_pk_fma_f32 v[52:53], v[136:137], v[158:159], v[52:53]
	v_mov_b32_dpp v115, v55 row_shr:2 row_mask:0xf bank_mask:0xf
	v_pk_fma_f32 v[50:51], v[58:59], v[106:107], v[50:51]
	v_pk_fma_f32 v[144:145], v[98:99], v[148:149], v[144:145]
	v_pk_fma_f32 v[48:49], v[142:143], v[156:157], v[48:49]
	v_pk_fma_f32 v[52:53], v[140:141], v[162:163], v[52:53]
	v_pk_fma_f32 v[50:51], v[62:63], v[114:115], v[50:51]
	v_mul_f32_e32 v55, 0xbfb8aa3b, v48
	v_exp_f32_e32 v55, v55
	v_mul_f32_e32 v54, 0xbfb8aa3b, v144
	v_exp_f32_e32 v54, v54
	v_add_f32_e32 v55, 1.0, v55
	v_rcp_f32_e32 v55, v55
	v_add_f32_e32 v54, 1.0, v54
	v_rcp_f32_e32 v54, v54
	v_mul_f32_e32 v48, v48, v55
	v_mul_f32_e32 v48, v48, v49
	v_mul_f32_e32 v49, 0xbfb8aa3b, v52
	v_exp_f32_e32 v49, v49
	v_mul_f32_e32 v54, v144, v54
	v_mul_f32_e32 v54, v54, v145
	v_cvt_pk_bf16_f32 v114, v54, v48
	v_add_f32_e32 v49, 1.0, v49
	v_rcp_f32_e32 v49, v49
	v_add_u32_e32 v48, 0xb000, v56
	v_mul_f32_e32 v49, v52, v49
	v_mul_f32_e32 v52, 0xbfb8aa3b, v50
	v_exp_f32_e32 v52, v52
	v_mul_f32_e32 v49, v49, v53
	v_add_f32_e32 v52, 1.0, v52
	v_rcp_f32_e32 v52, v52
	s_nop 0
	v_mul_f32_e32 v50, v50, v52
	v_mul_f32_e32 v50, v50, v51
	v_cvt_pk_bf16_f32 v115, v49, v50
	v_mov_b32_e32 v49, v189
	v_lshl_add_u64 v[48:49], v[48:49], 1, s[4:5]
	global_store_dwordx4 v[48:49], v[112:115], off
	v_mad_u32_u24 v52, v187, s1, v146
	v_add_u32_e32 v48, s3, v52
	v_mov_b32_e32 v49, v189
	v_lshl_add_u64 v[48:49], v[48:49], 2, s[6:7]
	global_load_dwordx4 v[48:51], v[48:49], off
	v_mov_b32_e32 v106, v189
	v_mov_b32_e32 v112, v189
	v_mov_b32_e32 v122, v189
	v_mov_b32_e32 v144, v189
	v_mov_b32_e32 v114, v189
	v_mov_b32_e32 v120, v189
	s_waitcnt vmcnt(0)
	v_mov_b32_dpp v106, v48 row_ror:1 row_mask:0xf bank_mask:0xf
	v_mov_b32_dpp v112, v48 row_ror:2 row_mask:0xf bank_mask:0xf
	v_mov_b32_dpp v122, v50 row_ror:1 row_mask:0xf bank_mask:0xf
	v_mov_b32_dpp v144, v50 row_ror:2 row_mask:0xf bank_mask:0xf
	v_mov_b32_e32 v48, v189
	v_mov_b32_e32 v50, v189
	v_mov_b32_dpp v114, v49 row_ror:1 row_mask:0xf bank_mask:0xf
	v_mov_b32_dpp v120, v49 row_ror:2 row_mask:0xf bank_mask:0xf
	v_mov_b32_dpp v48, v51 row_ror:1 row_mask:0xf bank_mask:0xf
	v_mov_b32_dpp v50, v51 row_ror:2 row_mask:0xf bank_mask:0xf
	v_mov_b32_dpp v106, v40 row_shr:1 row_mask:0xf bank_mask:0xf
	v_mov_b32_dpp v112, v40 row_shr:2 row_mask:0xf bank_mask:0xf
	v_mov_b32_dpp v114, v41 row_shr:1 row_mask:0xf bank_mask:0xf
	v_mov_b32_dpp v120, v41 row_shr:2 row_mask:0xf bank_mask:0xf
	v_mov_b32_dpp v122, v42 row_shr:1 row_mask:0xf bank_mask:0xf
	v_mov_b32_dpp v144, v42 row_shr:2 row_mask:0xf bank_mask:0xf
	v_mov_b32_dpp v48, v43 row_shr:1 row_mask:0xf bank_mask:0xf
	v_mov_b32_dpp v50, v43 row_shr:2 row_mask:0xf bank_mask:0xf
	v_add_u32_e32 v52, s2, v52
	v_mov_b32_e32 v53, v189
	v_lshl_add_u64 v[52:53], v[52:53], 2, s[6:7]
	global_load_dwordx4 v[52:55], v[52:53], off
	v_mov_b32_e32 v107, v189
	v_mov_b32_e32 v113, v189
	v_mov_b32_e32 v115, v189
	v_mov_b32_e32 v121, v189
	v_mov_b32_e32 v123, v189
	v_mov_b32_e32 v145, v189
	v_mov_b32_e32 v149, v44
	v_mov_b32_e32 v49, v189
	v_mov_b32_e32 v148, v40
	v_mov_b32_e32 v51, v189
	v_pk_fma_f32 v[148:149], v[148:149], v[74:75], v[82:83]
	s_waitcnt vmcnt(0)
;     template <bool SAMP, bool BND>
;     __device__ __forceinline__ void conv_act(const f32x4 (&acc)[2][2][4][2], const Unit& u, int wr, int fr, int rbase, int ccol, LAS float* halo, const LAS float* wl_) const {
;     ...
;             for (int ai = 0; ai < 2; ++ai)
; #pragma unroll
;                 for (int m = 0; m < 4; ++m) {
;                     const int row = rbase + 128 * ai + 16 * m + fr;
;                     const bool ok = SAMP || (row < NP && !(ai == 0 && m == 0 && wr == 0 && fr < 2));
;                     const int t4 = (row + 2) & 2047;
;                     const float z1 = (BND && t4 == 2) ? 0.f : 1.f, z2 = (BND && (t4 == 2 || t4 == 3)) ? 0.f : 1.f;
;                     f32x4 a[2];
; #pragma unroll
;                     for (int bj = 0; bj < 2; ++bj) {
;                         f32x4 prev;
;                         if (SAMP) { const int s = (rbase + 128 * ai + 16 * m - NP) >> 4; prev = *(const f32x4*)(sffn + (unsigned)((s * 2 + (fr & 1)) * UPW + bj * DFF + u.pn * 128 + ccol + 4 * n)); }
;                         else if (m > 0) prev = acc[ai][bj][m > 0 ? m - 1 : 0][n];
;                         else { const int blk = 2 * ai + wr; prev = (f32x4){0.f, 0.f, 0.f, 0.f}; if (blk > 0) prev = *(const LAS f32x4*)(halo + ((blk - 1) * 2 + (fr & 1)) * 256 + bj * 128 + ccol + 4 * n); }
;                         const f32x4 cur = acc[ai][bj][m][n];
; #pragma unroll
;                         for (int j = 0; j < 4; ++j) {
;                             const float p1 = dppf<0x111>(dppf<0x121>(0.f, prev[j]), cur[j]);
;                             const float p2 = dppf<0x112>(dppf<0x122>(0.f, prev[j]), cur[j]);
;                             a[bj][j] = BB[bj][j] + W2[bj][j] * cur[j] + W1[bj][j] * (BND ? p1 * z1 : p1) + W0[bj][j] * (BND ? p2 * z2 : p2);
;                         }
;                         if (BND) { if (ok && t4 < 2 && row >= 2046) *(f32x4*)(offp + (unsigned)(((((row + 2) >> 11) - 1) * 2 + t4) * UPW + bj * DFF + u.pn * 128 + ccol + 4 * n)) = cur; }
;                         __builtin_amdgcn_sched_barrier(0);
;                     }
;                     float o[4];
; #pragma unroll
;                     for (int j = 0; j < 4; ++j) { const float g = a[0][j], v = a[1][j]; o[j] = g * __builtin_amdgcn_rcpf(1.0f + __builtin_amdgcn_exp2f(-g * LOG2E)) * v; }
;                     u32x2 w; w.x = cvt_pk_bf16(o[0], o[1]); w.y = cvt_pk_bf16(o[2], o[3]);
	v_mov_b32_dpp v107, v52 row_ror:1 row_mask:0xf bank_mask:0xf
	v_mov_b32_dpp v113, v52 row_ror:2 row_mask:0xf bank_mask:0xf
	s_nop 0
	v_mov_b32_dpp v107, v44 row_shr:1 row_mask:0xf bank_mask:0xf
	v_mov_b32_dpp v115, v53 row_ror:1 row_mask:0xf bank_mask:0xf
	v_mov_b32_dpp v113, v44 row_shr:2 row_mask:0xf bank_mask:0xf
	v_mov_b32_dpp v121, v53 row_ror:2 row_mask:0xf bank_mask:0xf
	v_mov_b32_e32 v44, v41
	v_mov_b32_dpp v123, v54 row_ror:1 row_mask:0xf bank_mask:0xf
	v_mov_b32_dpp v145, v54 row_ror:2 row_mask:0xf bank_mask:0xf
	v_mov_b32_dpp v115, v45 row_shr:1 row_mask:0xf bank_mask:0xf
	v_mov_b32_dpp v121, v45 row_shr:2 row_mask:0xf bank_mask:0xf
	v_pk_fma_f32 v[40:41], v[44:45], v[132:133], v[134:135]
	v_mov_b32_dpp v123, v46 row_shr:1 row_mask:0xf bank_mask:0xf
	v_mov_b32_dpp v145, v46 row_shr:2 row_mask:0xf bank_mask:0xf
	v_mov_b32_e32 v44, v42
	v_mov_b32_e32 v45, v46
	v_mov_b32_dpp v49, v55 row_ror:1 row_mask:0xf bank_mask:0xf
	v_mov_b32_e32 v46, v43
	v_pk_fma_f32 v[44:45], v[44:45], v[128:129], v[130:131]
	v_mov_b32_dpp v49, v47 row_shr:1 row_mask:0xf bank_mask:0xf
	v_mov_b32_dpp v51, v55 row_ror:2 row_mask:0xf bank_mask:0xf
	v_pk_fma_f32 v[42:43], v[46:47], v[60:61], v[70:71]
	v_pk_fma_f32 v[106:107], v[90:91], v[106:107], v[148:149]
	v_pk_fma_f32 v[40:41], v[138:139], v[114:115], v[40:41]
	v_pk_fma_f32 v[44:45], v[136:137], v[122:123], v[44:45]
	v_mov_b32_dpp v51, v47 row_shr:2 row_mask:0xf bank_mask:0xf
	v_pk_fma_f32 v[42:43], v[58:59], v[48:49], v[42:43]
	v_pk_fma_f32 v[106:107], v[98:99], v[112:113], v[106:107]
	v_pk_fma_f32 v[40:41], v[142:143], v[120:121], v[40:41]
	v_pk_fma_f32 v[44:45], v[140:141], v[144:145], v[44:45]
	v_pk_fma_f32 v[42:43], v[62:63], v[50:51], v[42:43]
	v_mul_f32_e32 v47, 0xbfb8aa3b, v40
	v_exp_f32_e32 v47, v47
	v_mul_f32_e32 v46, 0xbfb8aa3b, v106
	v_exp_f32_e32 v46, v46
	v_add_f32_e32 v47, 1.0, v47
	v_rcp_f32_e32 v47, v47
	v_add_f32_e32 v46, 1.0, v46
	v_rcp_f32_e32 v46, v46
	v_mul_f32_e32 v40, v40, v47
	v_mul_f32_e32 v40, v40, v41
	v_mul_f32_e32 v41, 0xbfb8aa3b, v44
	v_exp_f32_e32 v41, v41
	v_mul_f32_e32 v46, v106, v46
	v_mul_f32_e32 v46, v46, v107
	v_cvt_pk_bf16_f32 v106, v46, v40
	v_add_f32_e32 v41, 1.0, v41
	v_rcp_f32_e32 v41, v41
	v_add_u32_e32 v40, 0x16000, v56
	v_mul_f32_e32 v41, v44, v41
	v_mul_f32_e32 v44, 0xbfb8aa3b, v42
	v_exp_f32_e32 v44, v44
	v_mul_f32_e32 v41, v41, v45
	v_add_f32_e32 v44, 1.0, v44
	v_rcp_f32_e32 v44, v44
	s_nop 0
	v_mul_f32_e32 v42, v42, v44
	v_mul_f32_e32 v42, v42, v43
	v_cvt_pk_bf16_f32 v107, v41, v42
	v_mov_b32_e32 v41, v189
	v_lshl_add_u64 v[40:41], v[40:41], 1, s[4:5]
	global_store_dwordx4 v[40:41], v[104:107], off
	v_mad_u32_u24 v44, v186, s1, v146
	v_add_u32_e32 v40, s3, v44
	v_mov_b32_e32 v41, v189
	v_lshl_add_u64 v[40:41], v[40:41], 2, s[6:7]
	global_load_dwordx4 v[40:43], v[40:41], off
	v_mov_b32_e32 v48, v189
	v_mov_b32_e32 v50, v189
	v_mov_b32_e32 v104, v189
	v_mov_b32_e32 v106, v189
	v_mov_b32_e32 v52, v189
	v_mov_b32_e32 v54, v189
	s_waitcnt vmcnt(0)
	v_mov_b32_dpp v48, v40 row_ror:1 row_mask:0xf bank_mask:0xf
	v_mov_b32_dpp v50, v40 row_ror:2 row_mask:0xf bank_mask:0xf
	v_mov_b32_dpp v104, v42 row_ror:1 row_mask:0xf bank_mask:0xf
	v_mov_b32_dpp v106, v42 row_ror:2 row_mask:0xf bank_mask:0xf
	v_mov_b32_e32 v40, v189
	v_mov_b32_e32 v42, v189
	v_mov_b32_dpp v52, v41 row_ror:1 row_mask:0xf bank_mask:0xf
	v_mov_b32_dpp v54, v41 row_ror:2 row_mask:0xf bank_mask:0xf
	v_mov_b32_dpp v40, v43 row_ror:1 row_mask:0xf bank_mask:0xf
	v_mov_b32_dpp v42, v43 row_ror:2 row_mask:0xf bank_mask:0xf
	v_mov_b32_dpp v48, v32 row_shr:1 row_mask:0xf bank_mask:0xf
	v_mov_b32_dpp v50, v32 row_shr:2 row_mask:0xf bank_mask:0xf
	v_mov_b32_dpp v52, v33 row_shr:1 row_mask:0xf bank_mask:0xf
	v_mov_b32_dpp v54, v33 row_shr:2 row_mask:0xf bank_mask:0xf
	v_mov_b32_dpp v104, v34 row_shr:1 row_mask:0xf bank_mask:0xf
	v_mov_b32_dpp v106, v34 row_shr:2 row_mask:0xf bank_mask:0xf
	v_mov_b32_dpp v40, v35 row_shr:1 row_mask:0xf bank_mask:0xf
	v_mov_b32_dpp v42, v35 row_shr:2 row_mask:0xf bank_mask:0xf
	v_add_u32_e32 v44, s2, v44
	v_mov_b32_e32 v45, v189
	v_lshl_add_u64 v[44:45], v[44:45], 2, s[6:7]
	global_load_dwordx4 v[44:47], v[44:45], off
	v_mov_b32_e32 v49, v189
	v_mov_b32_e32 v51, v189
	v_mov_b32_e32 v53, v189
	v_mov_b32_e32 v55, v189
	v_mov_b32_e32 v105, v189
	v_mov_b32_e32 v107, v189
	v_mov_b32_e32 v113, v36
	v_mov_b32_e32 v41, v189
	v_mov_b32_e32 v112, v32
	v_mov_b32_e32 v43, v189
	v_pk_fma_f32 v[74:75], v[112:113], v[74:75], v[82:83]
	s_waitcnt vmcnt(0)
;     template <bool SAMP, bool BND>
;     __device__ __forceinline__ void conv_act(const f32x4 (&acc)[2][2][4][2], const Unit& u, int wr, int fr, int rbase, int ccol, LAS float* halo, const LAS float* wl_) const {
;     ...
;             for (int ai = 0; ai < 2; ++ai)
; #pragma unroll
;                 for (int m = 0; m < 4; ++m) {
;                     const int row = rbase + 128 * ai + 16 * m + fr;
;                     const bool ok = SAMP || (row < NP && !(ai == 0 && m == 0 && wr == 0 && fr < 2));
;                     const int t4 = (row + 2) & 2047;
;                     const float z1 = (BND && t4 == 2) ? 0.f : 1.f, z2 = (BND && (t4 == 2 || t4 == 3)) ? 0.f : 1.f;
;                     f32x4 a[2];
; #pragma unroll
;                     for (int bj = 0; bj < 2; ++bj) {
;                         f32x4 prev;
;                         if (SAMP) { const int s = (rbase + 128 * ai + 16 * m - NP) >> 4; prev = *(const f32x4*)(sffn + (unsigned)((s * 2 + (fr & 1)) * UPW + bj * DFF + u.pn * 128 + ccol + 4 * n)); }
;                         else if (m > 0) prev = acc[ai][bj][m > 0 ? m - 1 : 0][n];
;                         else { const int blk = 2 * ai + wr; prev = (f32x4){0.f, 0.f, 0.f, 0.f}; if (blk > 0) prev = *(const LAS f32x4*)(halo + ((blk - 1) * 2 + (fr & 1)) * 256 + bj * 128 + ccol + 4 * n); }
;                         const f32x4 cur = acc[ai][bj][m][n];
; #pragma unroll
;                         for (int j = 0; j < 4; ++j) {
;                             const float p1 = dppf<0x111>(dppf<0x121>(0.f, prev[j]), cur[j]);
;                             const float p2 = dppf<0x112>(dppf<0x122>(0.f, prev[j]), cur[j]);
;                             a[bj][j] = BB[bj][j] + W2[bj][j] * cur[j] + W1[bj][j] * (BND ? p1 * z1 : p1) + W0[bj][j] * (BND ? p2 * z2 : p2);
;                         }
;                         if (BND) { if (ok && t4 < 2 && row >= 2046) *(f32x4*)(offp + (unsigned)(((((row + 2) >> 11) - 1) * 2 + t4) * UPW + bj * DFF + u.pn * 128 + ccol + 4 * n)) = cur; }
;                         __builtin_amdgcn_sched_barrier(0);
;                     }
;                     float o[4];
; #pragma unroll
;                     for (int j = 0; j < 4; ++j) { const float g = a[0][j], v = a[1][j]; o[j] = g * __builtin_amdgcn_rcpf(1.0f + __builtin_amdgcn_exp2f(-g * LOG2E)) * v; }
;                     u32x2 w; w.x = cvt_pk_bf16(o[0], o[1]); w.y = cvt_pk_bf16(o[2], o[3]);
	v_mov_b32_dpp v49, v44 row_ror:1 row_mask:0xf bank_mask:0xf
	v_mov_b32_dpp v51, v44 row_ror:2 row_mask:0xf bank_mask:0xf
	s_nop 0
	v_mov_b32_dpp v49, v36 row_shr:1 row_mask:0xf bank_mask:0xf
	v_mov_b32_dpp v53, v45 row_ror:1 row_mask:0xf bank_mask:0xf
	v_mov_b32_dpp v51, v36 row_shr:2 row_mask:0xf bank_mask:0xf
	v_mov_b32_dpp v55, v45 row_ror:2 row_mask:0xf bank_mask:0xf
	v_mov_b32_e32 v36, v33
	v_mov_b32_dpp v105, v46 row_ror:1 row_mask:0xf bank_mask:0xf
	v_mov_b32_dpp v107, v46 row_ror:2 row_mask:0xf bank_mask:0xf
	v_mov_b32_dpp v53, v37 row_shr:1 row_mask:0xf bank_mask:0xf
	v_mov_b32_dpp v55, v37 row_shr:2 row_mask:0xf bank_mask:0xf
	v_pk_fma_f32 v[32:33], v[36:37], v[132:133], v[134:135]
	v_mov_b32_dpp v105, v38 row_shr:1 row_mask:0xf bank_mask:0xf
	v_mov_b32_dpp v107, v38 row_shr:2 row_mask:0xf bank_mask:0xf
	v_mov_b32_e32 v36, v34
	v_mov_b32_e32 v37, v38
	v_mov_b32_dpp v41, v47 row_ror:1 row_mask:0xf bank_mask:0xf
	v_mov_b32_e32 v38, v35
	v_pk_fma_f32 v[36:37], v[36:37], v[128:129], v[130:131]
	v_mov_b32_dpp v41, v39 row_shr:1 row_mask:0xf bank_mask:0xf
	v_mov_b32_dpp v43, v47 row_ror:2 row_mask:0xf bank_mask:0xf
	v_pk_fma_f32 v[34:35], v[38:39], v[60:61], v[70:71]
	v_pk_fma_f32 v[48:49], v[90:91], v[48:49], v[74:75]
	v_pk_fma_f32 v[32:33], v[138:139], v[52:53], v[32:33]
	v_pk_fma_f32 v[36:37], v[136:137], v[104:105], v[36:37]
	v_mov_b32_dpp v43, v39 row_shr:2 row_mask:0xf bank_mask:0xf
	v_pk_fma_f32 v[34:35], v[58:59], v[40:41], v[34:35]
	v_pk_fma_f32 v[48:49], v[98:99], v[50:51], v[48:49]
	v_pk_fma_f32 v[32:33], v[142:143], v[54:55], v[32:33]
	v_pk_fma_f32 v[36:37], v[140:141], v[106:107], v[36:37]
	v_pk_fma_f32 v[34:35], v[62:63], v[42:43], v[34:35]
	v_mul_f32_e32 v39, 0xbfb8aa3b, v32
	v_exp_f32_e32 v39, v39
	v_mul_f32_e32 v38, 0xbfb8aa3b, v48
	v_exp_f32_e32 v38, v38
	v_add_f32_e32 v39, 1.0, v39
	v_rcp_f32_e32 v39, v39
	v_add_f32_e32 v38, 1.0, v38
	v_rcp_f32_e32 v38, v38
	v_mul_f32_e32 v32, v32, v39
	v_mul_f32_e32 v32, v32, v33
	v_mul_f32_e32 v33, 0xbfb8aa3b, v36
	v_exp_f32_e32 v33, v33
	v_mul_f32_e32 v38, v48, v38
	v_mul_f32_e32 v38, v38, v49
	v_cvt_pk_bf16_f32 v98, v38, v32
	v_add_f32_e32 v33, 1.0, v33
	v_rcp_f32_e32 v33, v33
	v_add_u32_e32 v32, 0x21000, v56
	v_mul_f32_e32 v33, v36, v33
	v_mul_f32_e32 v36, 0xbfb8aa3b, v34
	v_exp_f32_e32 v36, v36
	v_mul_f32_e32 v33, v33, v37
	v_add_f32_e32 v36, 1.0, v36
	v_rcp_f32_e32 v36, v36
	s_nop 0
	v_mul_f32_e32 v34, v34, v36
	v_mul_f32_e32 v34, v34, v35
	v_cvt_pk_bf16_f32 v99, v33, v34
	v_mov_b32_e32 v33, v189
	v_lshl_add_u64 v[32:33], v[32:33], 1, s[4:5]
	global_store_dwordx4 v[32:33], v[96:99], off
	v_mad_u32_u24 v40, v160, s1, v146
	v_add_u32_e32 v32, s3, v40
	v_mov_b32_e32 v33, v189
	v_lshl_add_u64 v[32:33], v[32:33], 2, s[6:7]
	global_load_dwordx4 v[34:37], v[32:33], off
	v_mov_b32_e32 v38, v189
	v_mov_b32_e32 v39, v189
	v_mov_b32_e32 v32, v124
	v_mov_b32_e32 v33, v100
	v_mov_b32_e32 v100, v125
	s_waitcnt vmcnt(0)
	v_mov_b32_dpp v38, v34 row_ror:1 row_mask:0xf bank_mask:0xf
	v_mov_b32_dpp v39, v34 row_ror:2 row_mask:0xf bank_mask:0xf
	s_nop 0
	v_mov_b32_dpp v38, v28 row_shr:1 row_mask:0xf bank_mask:0xf
	v_fma_f32 v34, v29, v109, v93
	v_mov_b32_dpp v39, v28 row_shr:2 row_mask:0xf bank_mask:0xf
	v_fma_f32 v28, v28, v108, v92
	v_pk_mul_f32 v[38:39], v[32:33], v[38:39]
	s_nop 0
	v_add_f32_e32 v28, v28, v38
	v_add_f32_e32 v41, v28, v39
	v_mov_b32_e32 v38, v189
	v_mov_b32_e32 v39, v189
	s_nop 0
	v_mov_b32_dpp v38, v35 row_ror:1 row_mask:0xf bank_mask:0xf
	v_mov_b32_dpp v39, v35 row_ror:2 row_mask:0xf bank_mask:0xf
	v_mov_b32_e32 v35, v189
	v_mov_b32_dpp v38, v29 row_shr:1 row_mask:0xf bank_mask:0xf
	v_mov_b32_dpp v39, v29 row_shr:2 row_mask:0xf bank_mask:0xf
	v_pk_mul_f32 v[28:29], v[100:101], v[38:39]
	v_mov_b32_dpp v35, v36 row_ror:2 row_mask:0xf bank_mask:0xf
	v_add_f32_e32 v28, v34, v28
	v_mov_b32_e32 v34, v189
	v_add_f32_e32 v42, v28, v29
	v_mov_b32_dpp v35, v30 row_shr:2 row_mask:0xf bank_mask:0xf
	v_mov_b32_dpp v34, v36 row_ror:1 row_mask:0xf bank_mask:0xf
	v_mov_b32_e32 v28, v126
	v_mov_b32_e32 v29, v102
	v_mov_b32_dpp v34, v30 row_shr:1 row_mask:0xf bank_mask:0xf
	v_fma_f32 v30, v30, v110, v94
	v_pk_mul_f32 v[34:35], v[28:29], v[34:35]
	v_mov_b32_e32 v102, v127
	v_add_f32_e32 v30, v30, v34
	v_add_f32_e32 v43, v30, v35
	v_mov_b32_e32 v34, v189
	v_mov_b32_e32 v35, v189
	v_fma_f32 v36, v31, v111, v95
	v_mov_b32_dpp v34, v37 row_ror:1 row_mask:0xf bank_mask:0xf
	v_mov_b32_dpp v35, v37 row_ror:2 row_mask:0xf bank_mask:0xf
	s_nop 0
	v_mov_b32_dpp v34, v31 row_shr:1 row_mask:0xf bank_mask:0xf
	v_mov_b32_dpp v35, v31 row_shr:2 row_mask:0xf bank_mask:0xf
	v_pk_mul_f32 v[30:31], v[102:103], v[34:35]
	s_nop 0
	v_add_f32_e32 v30, v36, v30
	v_add_f32_e32 v44, v30, v31
	v_add_u32_e32 v30, s2, v40
	v_mov_b32_e32 v31, v189
	v_lshl_add_u64 v[30:31], v[30:31], 2, s[6:7]
	global_load_dwordx4 v[34:37], v[30:31], off
	v_mov_b32_e32 v38, v189
	v_mov_b32_e32 v39, v189
	v_mov_b32_e32 v30, v116
	v_mov_b32_e32 v31, v76
	v_mov_b32_e32 v76, v117
	s_waitcnt vmcnt(0)
; #define LAS __attribute__((address_space(3)))
; __device__ __forceinline__ unsigned cvt_pk_bf16(float lo, float hi) { unsigned r; asm volatile("v_cvt_pk_bf16_f32 %0, %1, %2" : "=v"(r) : "v"(lo), "v"(hi)); return r; }
;     template <bool SAMP, bool BND>
;     __device__ __forceinline__ void conv_act(const f32x4 (&acc)[2][2][4][2], const Unit& u, int wr, int fr, int rbase, int ccol, LAS float* halo, const LAS float* wl_) const {
;     ...
;                     for (int bj = 0; bj < 2; ++bj) {
;                         f32x4 prev;
;                         if (SAMP) { const int s = (rbase + 128 * ai + 16 * m - NP) >> 4; prev = *(const f32x4*)(sffn + (unsigned)((s * 2 + (fr & 1)) * UPW + bj * DFF + u.pn * 128 + ccol + 4 * n)); }
;                         else if (m > 0) prev = acc[ai][bj][m > 0 ? m - 1 : 0][n];
;                         else { const int blk = 2 * ai + wr; prev = (f32x4){0.f, 0.f, 0.f, 0.f}; if (blk > 0) prev = *(const LAS f32x4*)(halo + ((blk - 1) * 2 + (fr & 1)) * 256 + bj * 128 + ccol + 4 * n); }
;                         const f32x4 cur = acc[ai][bj][m][n];
; #pragma unroll
;                         for (int j = 0; j < 4; ++j) {
;                             const float p1 = dppf<0x111>(dppf<0x121>(0.f, prev[j]), cur[j]);
;                             const float p2 = dppf<0x112>(dppf<0x122>(0.f, prev[j]), cur[j]);
;                             a[bj][j] = BB[bj][j] + W2[bj][j] * cur[j] + W1[bj][j] * (BND ? p1 * z1 : p1) + W0[bj][j] * (BND ? p2 * z2 : p2);
;                         }
;                         if (BND) { if (ok && t4 < 2 && row >= 2046) *(f32x4*)(offp + (unsigned)(((((row + 2) >> 11) - 1) * 2 + t4) * UPW + bj * DFF + u.pn * 128 + ccol + 4 * n)) = cur; }
;                         __builtin_amdgcn_sched_barrier(0);
;                     }
;                     float o[4];
; #pragma unroll
;                     for (int j = 0; j < 4; ++j) { const float g = a[0][j], v = a[1][j]; o[j] = g * __builtin_amdgcn_rcpf(1.0f + __builtin_amdgcn_exp2f(-g * LOG2E)) * v; }
;                     u32x2 w; w.x = cvt_pk_bf16(o[0], o[1]); w.y = cvt_pk_bf16(o[2], o[3]);
;                     if (n == 0) keep[ai][m] = w;
;                     else if (ok) { u32x4 w4; w4.x = keep[ai][m].x; w4.y = keep[ai][m].y; w4.z = w.x; w4.w = w.y; *(u32x4*)(ACT + (unsigned)(row * DFF + u.pn * 128 + ccol)) = w4; }
	v_mov_b32_dpp v38, v34 row_ror:1 row_mask:0xf bank_mask:0xf
	v_mov_b32_dpp v39, v34 row_ror:2 row_mask:0xf bank_mask:0xf
	s_nop 0
	v_mov_b32_dpp v38, v24 row_shr:1 row_mask:0xf bank_mask:0xf
	v_fma_f32 v34, v25, v85, v67
	v_mov_b32_dpp v39, v24 row_shr:2 row_mask:0xf bank_mask:0xf
	v_fma_f32 v24, v24, v84, v66
	v_pk_mul_f32 v[38:39], v[30:31], v[38:39]
	s_nop 0
	v_add_f32_e32 v24, v24, v38
	v_add_f32_e32 v40, v24, v39
	v_mov_b32_e32 v38, v189
	v_mov_b32_e32 v39, v189
	s_nop 0
	v_mov_b32_dpp v38, v35 row_ror:1 row_mask:0xf bank_mask:0xf
	v_mov_b32_dpp v39, v35 row_ror:2 row_mask:0xf bank_mask:0xf
	v_mov_b32_e32 v35, v189
	v_mov_b32_dpp v38, v25 row_shr:1 row_mask:0xf bank_mask:0xf
	v_mov_b32_dpp v39, v25 row_shr:2 row_mask:0xf bank_mask:0xf
	v_pk_mul_f32 v[24:25], v[76:77], v[38:39]
	v_mov_b32_dpp v35, v36 row_ror:2 row_mask:0xf bank_mask:0xf
	v_add_f32_e32 v24, v34, v24
	v_mov_b32_e32 v34, v189
	v_add_f32_e32 v38, v24, v25
	v_mov_b32_dpp v35, v26 row_shr:2 row_mask:0xf bank_mask:0xf
	v_mov_b32_dpp v34, v36 row_ror:1 row_mask:0xf bank_mask:0xf
	v_mov_b32_e32 v24, v118
	v_mov_b32_e32 v25, v78
	v_mov_b32_dpp v34, v26 row_shr:1 row_mask:0xf bank_mask:0xf
	v_fma_f32 v26, v26, v86, v68
	v_pk_mul_f32 v[34:35], v[24:25], v[34:35]
	v_mov_b32_e32 v78, v119
	v_add_f32_e32 v26, v26, v34
	v_add_f32_e32 v36, v26, v35
	v_mov_b32_e32 v34, v189
	v_mov_b32_e32 v35, v189
	s_nop 0
	v_mov_b32_dpp v34, v37 row_ror:1 row_mask:0xf bank_mask:0xf
	v_mov_b32_dpp v35, v37 row_ror:2 row_mask:0xf bank_mask:0xf
	v_fma_f32 v37, v27, v87, v69
	v_mov_b32_dpp v34, v27 row_shr:1 row_mask:0xf bank_mask:0xf
	v_mov_b32_dpp v35, v27 row_shr:2 row_mask:0xf bank_mask:0xf
	v_pk_mul_f32 v[26:27], v[78:79], v[34:35]
	s_nop 0
	v_add_f32_e32 v26, v37, v26
	v_add_f32_e32 v26, v26, v27
	v_mul_f32_e32 v35, 0xbfb8aa3b, v43
	v_exp_f32_e32 v35, v35
	v_mul_f32_e32 v27, 0xbfb8aa3b, v41
	v_exp_f32_e32 v27, v27
	v_mul_f32_e32 v34, 0xbfb8aa3b, v42
	v_add_f32_e32 v35, 1.0, v35
	v_rcp_f32_e32 v35, v35
	v_exp_f32_e32 v34, v34
	v_add_f32_e32 v27, 1.0, v27
	v_rcp_f32_e32 v27, v27
	v_mul_f32_e32 v35, v43, v35
	v_mul_f32_e32 v35, v35, v36
	v_mul_f32_e32 v36, 0xbfb8aa3b, v44
	v_exp_f32_e32 v36, v36
	v_add_f32_e32 v34, 1.0, v34
	v_rcp_f32_e32 v34, v34
	v_mul_f32_e32 v27, v41, v27
	v_add_f32_e32 v36, 1.0, v36
	v_rcp_f32_e32 v36, v36
	v_mul_f32_e32 v27, v27, v40
	v_mul_f32_e32 v34, v42, v34
	v_mul_f32_e32 v34, v34, v38
	v_mul_f32_e32 v36, v44, v36
	v_mul_f32_e32 v26, v36, v26
	v_cvt_pk_bf16_f32 v90, v27, v34
	v_cvt_pk_bf16_f32 v91, v35, v26
	v_add_u32_e32 v26, 0x58000, v56
	v_mov_b32_e32 v27, v189
	v_lshl_add_u64 v[26:27], v[26:27], 1, s[4:5]
	global_store_dwordx4 v[26:27], v[88:91], off
	v_mad_u32_u24 v38, v154, s1, v146
	v_add_u32_e32 v26, s3, v38
	v_mov_b32_e32 v27, v189
	v_lshl_add_u64 v[26:27], v[26:27], 2, s[6:7]
	global_load_dwordx4 v[34:37], v[26:27], off
	v_mov_b32_e32 v26, v189
	v_mov_b32_e32 v27, v189
	s_waitcnt vmcnt(0)
	v_mov_b32_dpp v26, v34 row_ror:1 row_mask:0xf bank_mask:0xf
	v_mov_b32_dpp v27, v34 row_ror:2 row_mask:0xf bank_mask:0xf
	s_nop 0
	v_mov_b32_dpp v26, v20 row_shr:1 row_mask:0xf bank_mask:0xf
	v_mov_b32_dpp v27, v20 row_shr:2 row_mask:0xf bank_mask:0xf
	v_fma_f32 v20, v20, v108, v92
	v_pk_mul_f32 v[26:27], v[32:33], v[26:27]
	s_nop 0
	v_add_f32_e32 v20, v20, v26
	v_add_f32_e32 v34, v20, v27
	v_mov_b32_e32 v26, v189
	v_mov_b32_e32 v27, v189
	s_nop 0
	v_mov_b32_dpp v26, v35 row_ror:1 row_mask:0xf bank_mask:0xf
	v_mov_b32_dpp v27, v35 row_ror:2 row_mask:0xf bank_mask:0xf
	v_fma_f32 v35, v21, v109, v93
	v_mov_b32_dpp v26, v21 row_shr:1 row_mask:0xf bank_mask:0xf
	v_mov_b32_dpp v27, v21 row_shr:2 row_mask:0xf bank_mask:0xf
	v_pk_mul_f32 v[20:21], v[100:101], v[26:27]
	s_nop 0
	v_add_f32_e32 v20, v35, v20
	v_add_f32_e32 v35, v20, v21
	v_mov_b32_e32 v20, v189
	v_mov_b32_e32 v21, v189
	s_nop 0
	v_mov_b32_dpp v20, v36 row_ror:1 row_mask:0xf bank_mask:0xf
	v_mov_b32_dpp v21, v36 row_ror:2 row_mask:0xf bank_mask:0xf
	s_nop 0
	v_mov_b32_dpp v20, v22 row_shr:1 row_mask:0xf bank_mask:0xf
	v_mov_b32_dpp v21, v22 row_shr:2 row_mask:0xf bank_mask:0xf
	v_fma_f32 v22, v22, v110, v94
	v_pk_mul_f32 v[20:21], v[28:29], v[20:21]
	s_nop 0
	v_add_f32_e32 v20, v22, v20
	v_add_f32_e32 v36, v20, v21
	v_mov_b32_e32 v20, v189
	v_mov_b32_e32 v21, v189
	v_fma_f32 v22, v23, v111, v95
	v_mov_b32_dpp v20, v37 row_ror:1 row_mask:0xf bank_mask:0xf
	v_mov_b32_dpp v21, v37 row_ror:2 row_mask:0xf bank_mask:0xf
	s_nop 0
	v_mov_b32_dpp v20, v23 row_shr:1 row_mask:0xf bank_mask:0xf
	v_mov_b32_dpp v21, v23 row_shr:2 row_mask:0xf bank_mask:0xf
	v_pk_mul_f32 v[20:21], v[102:103], v[20:21]
	s_nop 0
	v_add_f32_e32 v20, v22, v20
	v_add_f32_e32 v37, v20, v21
	v_add_u32_e32 v20, s2, v38
	v_mov_b32_e32 v21, v189
	v_lshl_add_u64 v[20:21], v[20:21], 2, s[6:7]
	global_load_dwordx4 v[20:23], v[20:21], off
	v_mov_b32_e32 v26, v189
	v_mov_b32_e32 v27, v189
	s_waitcnt vmcnt(0)
; #define LAS __attribute__((address_space(3)))
; __device__ __forceinline__ unsigned cvt_pk_bf16(float lo, float hi) { unsigned r; asm volatile("v_cvt_pk_bf16_f32 %0, %1, %2" : "=v"(r) : "v"(lo), "v"(hi)); return r; }
;     template <bool SAMP, bool BND>
;     __device__ __forceinline__ void conv_act(const f32x4 (&acc)[2][2][4][2], const Unit& u, int wr, int fr, int rbase, int ccol, LAS float* halo, const LAS float* wl_) const {
;     ...
;                     for (int bj = 0; bj < 2; ++bj) {
;                         f32x4 prev;
;                         if (SAMP) { const int s = (rbase + 128 * ai + 16 * m - NP) >> 4; prev = *(const f32x4*)(sffn + (unsigned)((s * 2 + (fr & 1)) * UPW + bj * DFF + u.pn * 128 + ccol + 4 * n)); }
;                         else if (m > 0) prev = acc[ai][bj][m > 0 ? m - 1 : 0][n];
;                         else { const int blk = 2 * ai + wr; prev = (f32x4){0.f, 0.f, 0.f, 0.f}; if (blk > 0) prev = *(const LAS f32x4*)(halo + ((blk - 1) * 2 + (fr & 1)) * 256 + bj * 128 + ccol + 4 * n); }
;                         const f32x4 cur = acc[ai][bj][m][n];
; #pragma unroll
;                         for (int j = 0; j < 4; ++j) {
;                             const float p1 = dppf<0x111>(dppf<0x121>(0.f, prev[j]), cur[j]);
;                             const float p2 = dppf<0x112>(dppf<0x122>(0.f, prev[j]), cur[j]);
;                             a[bj][j] = BB[bj][j] + W2[bj][j] * cur[j] + W1[bj][j] * (BND ? p1 * z1 : p1) + W0[bj][j] * (BND ? p2 * z2 : p2);
;                         }
;                         if (BND) { if (ok && t4 < 2 && row >= 2046) *(f32x4*)(offp + (unsigned)(((((row + 2) >> 11) - 1) * 2 + t4) * UPW + bj * DFF + u.pn * 128 + ccol + 4 * n)) = cur; }
;                         __builtin_amdgcn_sched_barrier(0);
;                     }
;                     float o[4];
; #pragma unroll
;                     for (int j = 0; j < 4; ++j) { const float g = a[0][j], v = a[1][j]; o[j] = g * __builtin_amdgcn_rcpf(1.0f + __builtin_amdgcn_exp2f(-g * LOG2E)) * v; }
;                     u32x2 w; w.x = cvt_pk_bf16(o[0], o[1]); w.y = cvt_pk_bf16(o[2], o[3]);
;                     if (n == 0) keep[ai][m] = w;
;                     else if (ok) { u32x4 w4; w4.x = keep[ai][m].x; w4.y = keep[ai][m].y; w4.z = w.x; w4.w = w.y; *(u32x4*)(ACT + (unsigned)(row * DFF + u.pn * 128 + ccol)) = w4; }
	v_mov_b32_dpp v26, v20 row_ror:1 row_mask:0xf bank_mask:0xf
	v_mov_b32_dpp v27, v20 row_ror:2 row_mask:0xf bank_mask:0xf
	s_nop 0
	v_mov_b32_dpp v26, v16 row_shr:1 row_mask:0xf bank_mask:0xf
	v_mov_b32_dpp v27, v16 row_shr:2 row_mask:0xf bank_mask:0xf
	v_fma_f32 v16, v16, v84, v66
	v_pk_mul_f32 v[26:27], v[30:31], v[26:27]
	s_nop 0
	v_add_f32_e32 v16, v16, v26
	v_add_f32_e32 v20, v16, v27
	v_mov_b32_e32 v26, v189
	v_mov_b32_e32 v27, v189
	s_nop 0
	v_mov_b32_dpp v26, v21 row_ror:1 row_mask:0xf bank_mask:0xf
	v_mov_b32_dpp v27, v21 row_ror:2 row_mask:0xf bank_mask:0xf
	v_fma_f32 v21, v17, v85, v67
	v_mov_b32_dpp v26, v17 row_shr:1 row_mask:0xf bank_mask:0xf
	v_mov_b32_dpp v27, v17 row_shr:2 row_mask:0xf bank_mask:0xf
	v_pk_mul_f32 v[16:17], v[76:77], v[26:27]
	s_nop 0
	v_add_f32_e32 v16, v21, v16
	v_add_f32_e32 v21, v16, v17
	v_mov_b32_e32 v16, v189
	v_mov_b32_e32 v17, v189
	s_nop 0
	v_mov_b32_dpp v16, v22 row_ror:1 row_mask:0xf bank_mask:0xf
	v_mov_b32_dpp v17, v22 row_ror:2 row_mask:0xf bank_mask:0xf
	s_nop 0
	v_mov_b32_dpp v16, v18 row_shr:1 row_mask:0xf bank_mask:0xf
	v_mov_b32_dpp v17, v18 row_shr:2 row_mask:0xf bank_mask:0xf
	v_fma_f32 v18, v18, v86, v68
	v_pk_mul_f32 v[16:17], v[24:25], v[16:17]
	s_nop 0
	v_add_f32_e32 v16, v18, v16
	v_add_f32_e32 v18, v16, v17
	v_mov_b32_e32 v16, v189
	v_mov_b32_e32 v17, v189
	s_nop 0
	v_mov_b32_dpp v16, v23 row_ror:1 row_mask:0xf bank_mask:0xf
	v_mov_b32_dpp v17, v23 row_ror:2 row_mask:0xf bank_mask:0xf
	s_nop 0
	v_mov_b32_dpp v16, v19 row_shr:1 row_mask:0xf bank_mask:0xf
	v_mov_b32_dpp v17, v19 row_shr:2 row_mask:0xf bank_mask:0xf
	v_fma_f32 v19, v19, v87, v69
	v_pk_mul_f32 v[16:17], v[78:79], v[16:17]
	s_nop 0
	v_add_f32_e32 v16, v19, v16
	v_add_f32_e32 v16, v16, v17
	v_mul_f32_e32 v17, 0xbfb8aa3b, v34
	v_exp_f32_e32 v17, v17
	v_mul_f32_e32 v19, 0xbfb8aa3b, v35
	v_exp_f32_e32 v19, v19
	v_add_f32_e32 v17, 1.0, v17
	v_rcp_f32_e32 v17, v17
	v_add_f32_e32 v19, 1.0, v19
	v_rcp_f32_e32 v19, v19
	v_mul_f32_e32 v17, v34, v17
	v_mul_f32_e32 v17, v17, v20
	v_mul_f32_e32 v20, 0xbfb8aa3b, v36
	v_exp_f32_e32 v20, v20
	v_mul_f32_e32 v19, v35, v19
	v_mul_f32_e32 v19, v19, v21
	v_cvt_pk_bf16_f32 v82, v17, v19
	v_add_f32_e32 v20, 1.0, v20
	v_rcp_f32_e32 v20, v20
	v_mov_b32_e32 v17, v189
	v_mul_f32_e32 v20, v36, v20
	v_mul_f32_e32 v18, v20, v18
	v_mul_f32_e32 v20, 0xbfb8aa3b, v37
	v_exp_f32_e32 v20, v20
	s_nop 0
	v_add_f32_e32 v20, 1.0, v20
	v_rcp_f32_e32 v20, v20
	s_nop 0
	v_mul_f32_e32 v20, v37, v20
	v_mul_f32_e32 v16, v20, v16
	v_cvt_pk_bf16_f32 v83, v18, v16
	v_add_u32_e32 v16, 0x63000, v56
	v_lshl_add_u64 v[16:17], v[16:17], 1, s[4:5]
	global_store_dwordx4 v[16:17], v[80:83], off
	v_mad_u32_u24 v22, v153, s1, v146
	v_add_u32_e32 v16, s3, v22
	v_mov_b32_e32 v17, v189
	v_lshl_add_u64 v[16:17], v[16:17], 2, s[6:7]
	global_load_dwordx4 v[16:19], v[16:17], off
	v_mov_b32_e32 v20, v189
	v_mov_b32_e32 v21, v189
	s_waitcnt vmcnt(0)
	v_mov_b32_dpp v20, v16 row_ror:1 row_mask:0xf bank_mask:0xf
	v_mov_b32_dpp v21, v16 row_ror:2 row_mask:0xf bank_mask:0xf
	s_nop 0
	v_mov_b32_dpp v20, v12 row_shr:1 row_mask:0xf bank_mask:0xf
	v_fma_f32 v16, v13, v109, v93
	v_mov_b32_dpp v21, v12 row_shr:2 row_mask:0xf bank_mask:0xf
	v_fma_f32 v12, v12, v108, v92
	v_pk_mul_f32 v[20:21], v[32:33], v[20:21]
	s_nop 0
	v_add_f32_e32 v12, v12, v20
	v_add_f32_e32 v23, v12, v21
	v_mov_b32_e32 v20, v189
	v_mov_b32_e32 v21, v189
	s_nop 0
	v_mov_b32_dpp v20, v17 row_ror:1 row_mask:0xf bank_mask:0xf
	v_mov_b32_dpp v21, v17 row_ror:2 row_mask:0xf bank_mask:0xf
	s_nop 0
	v_mov_b32_dpp v20, v13 row_shr:1 row_mask:0xf bank_mask:0xf
	v_mov_b32_dpp v21, v13 row_shr:2 row_mask:0xf bank_mask:0xf
	v_pk_mul_f32 v[12:13], v[100:101], v[20:21]
	s_nop 0
	v_add_f32_e32 v12, v16, v12
	v_add_f32_e32 v20, v12, v13
	v_mov_b32_e32 v12, v189
	v_mov_b32_e32 v13, v189
	s_nop 0
	v_mov_b32_dpp v12, v18 row_ror:1 row_mask:0xf bank_mask:0xf
	v_mov_b32_dpp v13, v18 row_ror:2 row_mask:0xf bank_mask:0xf
	s_nop 0
	v_mov_b32_dpp v12, v14 row_shr:1 row_mask:0xf bank_mask:0xf
	v_mov_b32_dpp v13, v14 row_shr:2 row_mask:0xf bank_mask:0xf
	v_fma_f32 v14, v14, v110, v94
	v_pk_mul_f32 v[12:13], v[28:29], v[12:13]
	s_nop 0
	v_add_f32_e32 v12, v14, v12
	v_add_f32_e32 v18, v12, v13
	v_mov_b32_e32 v12, v189
	v_mov_b32_e32 v13, v189
	v_fma_f32 v14, v15, v111, v95
	v_mov_b32_dpp v12, v19 row_ror:1 row_mask:0xf bank_mask:0xf
	v_mov_b32_dpp v13, v19 row_ror:2 row_mask:0xf bank_mask:0xf
	s_nop 0
	v_mov_b32_dpp v12, v15 row_shr:1 row_mask:0xf bank_mask:0xf
	v_mov_b32_dpp v13, v15 row_shr:2 row_mask:0xf bank_mask:0xf
	v_pk_mul_f32 v[12:13], v[102:103], v[12:13]
	s_nop 0
	v_add_f32_e32 v12, v14, v12
	v_add_f32_e32 v19, v12, v13
	v_add_u32_e32 v12, s2, v22
	v_mov_b32_e32 v13, v189
	v_lshl_add_u64 v[12:13], v[12:13], 2, s[6:7]
	global_load_dwordx4 v[12:15], v[12:13], off
	v_mov_b32_e32 v16, v189
	v_mov_b32_e32 v17, v189
	s_waitcnt vmcnt(0)
; #define LAS __attribute__((address_space(3)))
; __device__ __forceinline__ unsigned cvt_pk_bf16(float lo, float hi) { unsigned r; asm volatile("v_cvt_pk_bf16_f32 %0, %1, %2" : "=v"(r) : "v"(lo), "v"(hi)); return r; }
;     template <bool SAMP, bool BND>
;     __device__ __forceinline__ void conv_act(const f32x4 (&acc)[2][2][4][2], const Unit& u, int wr, int fr, int rbase, int ccol, LAS float* halo, const LAS float* wl_) const {
;     ...
;                     for (int bj = 0; bj < 2; ++bj) {
;                         f32x4 prev;
;                         if (SAMP) { const int s = (rbase + 128 * ai + 16 * m - NP) >> 4; prev = *(const f32x4*)(sffn + (unsigned)((s * 2 + (fr & 1)) * UPW + bj * DFF + u.pn * 128 + ccol + 4 * n)); }
;                         else if (m > 0) prev = acc[ai][bj][m > 0 ? m - 1 : 0][n];
;                         else { const int blk = 2 * ai + wr; prev = (f32x4){0.f, 0.f, 0.f, 0.f}; if (blk > 0) prev = *(const LAS f32x4*)(halo + ((blk - 1) * 2 + (fr & 1)) * 256 + bj * 128 + ccol + 4 * n); }
;                         const f32x4 cur = acc[ai][bj][m][n];
; #pragma unroll
;                         for (int j = 0; j < 4; ++j) {
;                             const float p1 = dppf<0x111>(dppf<0x121>(0.f, prev[j]), cur[j]);
;                             const float p2 = dppf<0x112>(dppf<0x122>(0.f, prev[j]), cur[j]);
;                             a[bj][j] = BB[bj][j] + W2[bj][j] * cur[j] + W1[bj][j] * (BND ? p1 * z1 : p1) + W0[bj][j] * (BND ? p2 * z2 : p2);
;                         }
;                         if (BND) { if (ok && t4 < 2 && row >= 2046) *(f32x4*)(offp + (unsigned)(((((row + 2) >> 11) - 1) * 2 + t4) * UPW + bj * DFF + u.pn * 128 + ccol + 4 * n)) = cur; }
;                         __builtin_amdgcn_sched_barrier(0);
;                     }
;                     float o[4];
; #pragma unroll
;                     for (int j = 0; j < 4; ++j) { const float g = a[0][j], v = a[1][j]; o[j] = g * __builtin_amdgcn_rcpf(1.0f + __builtin_amdgcn_exp2f(-g * LOG2E)) * v; }
;                     u32x2 w; w.x = cvt_pk_bf16(o[0], o[1]); w.y = cvt_pk_bf16(o[2], o[3]);
;                     if (n == 0) keep[ai][m] = w;
;                     else if (ok) { u32x4 w4; w4.x = keep[ai][m].x; w4.y = keep[ai][m].y; w4.z = w.x; w4.w = w.y; *(u32x4*)(ACT + (unsigned)(row * DFF + u.pn * 128 + ccol)) = w4; }
	v_mov_b32_dpp v16, v12 row_ror:1 row_mask:0xf bank_mask:0xf
	v_mov_b32_dpp v17, v12 row_ror:2 row_mask:0xf bank_mask:0xf
	s_nop 0
	v_mov_b32_dpp v16, v8 row_shr:1 row_mask:0xf bank_mask:0xf
	v_mov_b32_dpp v17, v8 row_shr:2 row_mask:0xf bank_mask:0xf
	v_fma_f32 v8, v8, v84, v66
	v_pk_mul_f32 v[16:17], v[30:31], v[16:17]
	s_nop 0
	v_add_f32_e32 v8, v8, v16
	v_add_f32_e32 v12, v8, v17
	v_mov_b32_e32 v16, v189
	v_mov_b32_e32 v17, v189
	s_nop 0
	v_mov_b32_dpp v16, v13 row_ror:1 row_mask:0xf bank_mask:0xf
	v_mov_b32_dpp v17, v13 row_ror:2 row_mask:0xf bank_mask:0xf
	v_fma_f32 v13, v9, v85, v67
	v_mov_b32_dpp v16, v9 row_shr:1 row_mask:0xf bank_mask:0xf
	v_mov_b32_dpp v17, v9 row_shr:2 row_mask:0xf bank_mask:0xf
	v_pk_mul_f32 v[8:9], v[76:77], v[16:17]
	s_nop 0
	v_add_f32_e32 v8, v13, v8
	v_add_f32_e32 v13, v8, v9
	v_mov_b32_e32 v8, v189
	v_mov_b32_e32 v9, v189
	s_nop 0
	v_mov_b32_dpp v8, v14 row_ror:1 row_mask:0xf bank_mask:0xf
	v_mov_b32_dpp v9, v14 row_ror:2 row_mask:0xf bank_mask:0xf
	s_nop 0
	v_mov_b32_dpp v8, v10 row_shr:1 row_mask:0xf bank_mask:0xf
	v_mov_b32_dpp v9, v10 row_shr:2 row_mask:0xf bank_mask:0xf
	v_fma_f32 v10, v10, v86, v68
	v_pk_mul_f32 v[8:9], v[24:25], v[8:9]
	s_nop 0
	v_add_f32_e32 v8, v10, v8
	v_add_f32_e32 v10, v8, v9
	v_mov_b32_e32 v8, v189
	v_mov_b32_e32 v9, v189
	s_nop 0
	v_mov_b32_dpp v8, v15 row_ror:1 row_mask:0xf bank_mask:0xf
	v_mov_b32_dpp v9, v15 row_ror:2 row_mask:0xf bank_mask:0xf
	s_nop 0
	v_mov_b32_dpp v8, v11 row_shr:1 row_mask:0xf bank_mask:0xf
	v_mov_b32_dpp v9, v11 row_shr:2 row_mask:0xf bank_mask:0xf
	v_fma_f32 v11, v11, v87, v69
	v_pk_mul_f32 v[8:9], v[78:79], v[8:9]
	s_nop 0
	v_add_f32_e32 v8, v11, v8
	v_add_f32_e32 v8, v8, v9
	v_mul_f32_e32 v9, 0xbfb8aa3b, v23
	v_exp_f32_e32 v9, v9
	v_mul_f32_e32 v11, 0xbfb8aa3b, v20
	v_exp_f32_e32 v11, v11
	v_add_f32_e32 v9, 1.0, v9
	v_rcp_f32_e32 v9, v9
	v_add_f32_e32 v11, 1.0, v11
	v_rcp_f32_e32 v11, v11
	v_mul_f32_e32 v9, v23, v9
	v_mul_f32_e32 v9, v9, v12
	v_mul_f32_e32 v12, 0xbfb8aa3b, v18
	v_exp_f32_e32 v12, v12
	v_mul_f32_e32 v11, v20, v11
	v_mul_f32_e32 v11, v11, v13
	v_cvt_pk_bf16_f32 v74, v9, v11
	v_add_f32_e32 v12, 1.0, v12
	v_rcp_f32_e32 v12, v12
	v_mov_b32_e32 v9, v189
	v_mul_f32_e32 v12, v18, v12
	v_mul_f32_e32 v10, v12, v10
	v_mul_f32_e32 v12, 0xbfb8aa3b, v19
	v_exp_f32_e32 v12, v12
	s_nop 0
	v_add_f32_e32 v12, 1.0, v12
	v_rcp_f32_e32 v12, v12
	s_nop 0
	v_mul_f32_e32 v12, v19, v12
	v_mul_f32_e32 v8, v12, v8
	v_cvt_pk_bf16_f32 v75, v10, v8
	v_add_u32_e32 v8, 0x6e000, v56
	v_lshl_add_u64 v[8:9], v[8:9], 1, s[4:5]
	global_store_dwordx4 v[8:9], v[72:75], off
	v_mad_u32_u24 v14, v152, s1, v146
	v_add_u32_e32 v8, s3, v14
	v_mov_b32_e32 v9, v189
	v_lshl_add_u64 v[8:9], v[8:9], 2, s[6:7]
	global_load_dwordx4 v[8:11], v[8:9], off
	v_mov_b32_e32 v12, v189
	v_mov_b32_e32 v13, v189
	v_fmac_f32_e32 v95, v7, v111
	s_waitcnt vmcnt(0)
; #define LAS __attribute__((address_space(3)))
; __device__ __forceinline__ unsigned cvt_pk_bf16(float lo, float hi) { unsigned r; asm volatile("v_cvt_pk_bf16_f32 %0, %1, %2" : "=v"(r) : "v"(lo), "v"(hi)); return r; }
;     template <bool SAMP, bool BND>
;     __device__ __forceinline__ void conv_act(const f32x4 (&acc)[2][2][4][2], const Unit& u, int wr, int fr, int rbase, int ccol, LAS float* halo, const LAS float* wl_) const {
;     ...
;                     for (int bj = 0; bj < 2; ++bj) {
;                         f32x4 prev;
;                         if (SAMP) { const int s = (rbase + 128 * ai + 16 * m - NP) >> 4; prev = *(const f32x4*)(sffn + (unsigned)((s * 2 + (fr & 1)) * UPW + bj * DFF + u.pn * 128 + ccol + 4 * n)); }
;                         else if (m > 0) prev = acc[ai][bj][m > 0 ? m - 1 : 0][n];
;                         else { const int blk = 2 * ai + wr; prev = (f32x4){0.f, 0.f, 0.f, 0.f}; if (blk > 0) prev = *(const LAS f32x4*)(halo + ((blk - 1) * 2 + (fr & 1)) * 256 + bj * 128 + ccol + 4 * n); }
;                         const f32x4 cur = acc[ai][bj][m][n];
; #pragma unroll
;                         for (int j = 0; j < 4; ++j) {
;                             const float p1 = dppf<0x111>(dppf<0x121>(0.f, prev[j]), cur[j]);
;                             const float p2 = dppf<0x112>(dppf<0x122>(0.f, prev[j]), cur[j]);
;                             a[bj][j] = BB[bj][j] + W2[bj][j] * cur[j] + W1[bj][j] * (BND ? p1 * z1 : p1) + W0[bj][j] * (BND ? p2 * z2 : p2);
;                         }
;                         if (BND) { if (ok && t4 < 2 && row >= 2046) *(f32x4*)(offp + (unsigned)(((((row + 2) >> 11) - 1) * 2 + t4) * UPW + bj * DFF + u.pn * 128 + ccol + 4 * n)) = cur; }
;                         __builtin_amdgcn_sched_barrier(0);
;                     }
;                     float o[4];
; #pragma unroll
;                     for (int j = 0; j < 4; ++j) { const float g = a[0][j], v = a[1][j]; o[j] = g * __builtin_amdgcn_rcpf(1.0f + __builtin_amdgcn_exp2f(-g * LOG2E)) * v; }
;                     u32x2 w; w.x = cvt_pk_bf16(o[0], o[1]); w.y = cvt_pk_bf16(o[2], o[3]);
;                     if (n == 0) keep[ai][m] = w;
;                     else if (ok) { u32x4 w4; w4.x = keep[ai][m].x; w4.y = keep[ai][m].y; w4.z = w.x; w4.w = w.y; *(u32x4*)(ACT + (unsigned)(row * DFF + u.pn * 128 + ccol)) = w4; }
	v_mov_b32_dpp v12, v8 row_ror:1 row_mask:0xf bank_mask:0xf
	v_mov_b32_dpp v13, v8 row_ror:2 row_mask:0xf bank_mask:0xf
	s_nop 0
	v_mov_b32_dpp v12, v4 row_shr:1 row_mask:0xf bank_mask:0xf
	v_fma_f32 v8, v5, v109, v93
	v_mov_b32_dpp v13, v4 row_shr:2 row_mask:0xf bank_mask:0xf
	v_fma_f32 v4, v4, v108, v92
	v_pk_mul_f32 v[12:13], v[32:33], v[12:13]
	s_nop 0
	v_add_f32_e32 v4, v4, v12
	v_add_f32_e32 v15, v4, v13
	v_mov_b32_e32 v12, v189
	v_mov_b32_e32 v13, v189
	s_nop 0
	v_mov_b32_dpp v12, v9 row_ror:1 row_mask:0xf bank_mask:0xf
	v_mov_b32_dpp v13, v9 row_ror:2 row_mask:0xf bank_mask:0xf
	s_nop 0
	v_mov_b32_dpp v12, v5 row_shr:1 row_mask:0xf bank_mask:0xf
	v_mov_b32_dpp v13, v5 row_shr:2 row_mask:0xf bank_mask:0xf
	v_pk_mul_f32 v[4:5], v[100:101], v[12:13]
	s_nop 0
	v_add_f32_e32 v4, v8, v4
	v_add_f32_e32 v12, v4, v5
	v_mov_b32_e32 v4, v189
	v_mov_b32_e32 v5, v189
	s_nop 0
	v_mov_b32_dpp v4, v10 row_ror:1 row_mask:0xf bank_mask:0xf
	v_mov_b32_dpp v5, v10 row_ror:2 row_mask:0xf bank_mask:0xf
	s_nop 0
	v_mov_b32_dpp v4, v6 row_shr:1 row_mask:0xf bank_mask:0xf
	v_mov_b32_dpp v5, v6 row_shr:2 row_mask:0xf bank_mask:0xf
	v_fma_f32 v6, v6, v110, v94
	v_pk_mul_f32 v[4:5], v[28:29], v[4:5]
	s_nop 0
	v_add_f32_e32 v4, v6, v4
	v_add_f32_e32 v10, v4, v5
	v_mov_b32_e32 v4, v189
	v_mov_b32_e32 v5, v189
	s_nop 0
	v_mov_b32_dpp v4, v11 row_ror:1 row_mask:0xf bank_mask:0xf
	v_mov_b32_dpp v5, v11 row_ror:2 row_mask:0xf bank_mask:0xf
	s_nop 0
	v_mov_b32_dpp v4, v7 row_shr:1 row_mask:0xf bank_mask:0xf
	v_mov_b32_dpp v5, v7 row_shr:2 row_mask:0xf bank_mask:0xf
	v_pk_mul_f32 v[4:5], v[102:103], v[4:5]
	s_nop 0
	v_add_f32_e32 v4, v95, v4
	v_add_f32_e32 v11, v4, v5
	v_add_u32_e32 v4, s2, v14
	v_mov_b32_e32 v5, v189
	v_lshl_add_u64 v[4:5], v[4:5], 2, s[6:7]
	global_load_dwordx4 v[4:7], v[4:5], off
	v_mov_b32_e32 v8, v189
	v_mov_b32_e32 v9, v189
	v_fmac_f32_e32 v69, v3, v87
	s_waitcnt vmcnt(0)
	v_mov_b32_dpp v8, v4 row_ror:1 row_mask:0xf bank_mask:0xf
	v_mov_b32_dpp v9, v4 row_ror:2 row_mask:0xf bank_mask:0xf
	s_nop 0
	v_mov_b32_dpp v8, v0 row_shr:1 row_mask:0xf bank_mask:0xf
	v_mov_b32_dpp v9, v0 row_shr:2 row_mask:0xf bank_mask:0xf
	v_fma_f32 v0, v0, v84, v66
	v_pk_mul_f32 v[8:9], v[30:31], v[8:9]
	s_nop 0
	v_add_f32_e32 v0, v0, v8
	v_add_f32_e32 v4, v0, v9
	v_mov_b32_e32 v8, v189
	v_mov_b32_e32 v9, v189
	s_nop 0
	v_mov_b32_dpp v8, v5 row_ror:1 row_mask:0xf bank_mask:0xf
	v_mov_b32_dpp v9, v5 row_ror:2 row_mask:0xf bank_mask:0xf
	v_fma_f32 v5, v1, v85, v67
	v_mov_b32_dpp v8, v1 row_shr:1 row_mask:0xf bank_mask:0xf
	v_mov_b32_dpp v9, v1 row_shr:2 row_mask:0xf bank_mask:0xf
	v_pk_mul_f32 v[0:1], v[76:77], v[8:9]
	s_nop 0
	v_add_f32_e32 v0, v5, v0
	v_add_f32_e32 v5, v0, v1
	v_mov_b32_e32 v0, v189
	v_mov_b32_e32 v1, v189
	s_nop 0
	v_mov_b32_dpp v0, v6 row_ror:1 row_mask:0xf bank_mask:0xf
	v_mov_b32_dpp v1, v6 row_ror:2 row_mask:0xf bank_mask:0xf
	s_nop 0
	v_mov_b32_dpp v0, v2 row_shr:1 row_mask:0xf bank_mask:0xf
	v_mov_b32_dpp v1, v2 row_shr:2 row_mask:0xf bank_mask:0xf
	v_fma_f32 v2, v2, v86, v68
	v_pk_mul_f32 v[0:1], v[24:25], v[0:1]
	s_nop 0
	v_add_f32_e32 v0, v2, v0
	v_add_f32_e32 v2, v0, v1
	v_mov_b32_e32 v0, v189
	v_mov_b32_e32 v1, v189
	s_nop 0
	v_mov_b32_dpp v0, v7 row_ror:1 row_mask:0xf bank_mask:0xf
	v_mov_b32_dpp v1, v7 row_ror:2 row_mask:0xf bank_mask:0xf
	s_nop 0
	v_mov_b32_dpp v0, v3 row_shr:1 row_mask:0xf bank_mask:0xf
	v_mov_b32_dpp v1, v3 row_shr:2 row_mask:0xf bank_mask:0xf
	v_pk_mul_f32 v[0:1], v[78:79], v[0:1]
	s_nop 0
	v_add_f32_e32 v0, v69, v0
	v_add_f32_e32 v0, v0, v1
	v_mul_f32_e32 v1, 0xbfb8aa3b, v15
	v_exp_f32_e32 v1, v1
	v_mul_f32_e32 v3, 0xbfb8aa3b, v12
	v_exp_f32_e32 v3, v3
	v_add_f32_e32 v1, 1.0, v1
	v_rcp_f32_e32 v1, v1
	v_add_f32_e32 v3, 1.0, v3
	v_rcp_f32_e32 v3, v3
	v_mul_f32_e32 v1, v15, v1
	v_mul_f32_e32 v1, v1, v4
	v_mul_f32_e32 v4, 0xbfb8aa3b, v10
	v_exp_f32_e32 v4, v4
	v_mul_f32_e32 v3, v12, v3
	v_mul_f32_e32 v3, v3, v5
	v_cvt_pk_bf16_f32 v66, v1, v3
	v_add_f32_e32 v4, 1.0, v4
	v_rcp_f32_e32 v4, v4
	v_mov_b32_e32 v1, v189
	v_mul_f32_e32 v4, v10, v4
	v_mul_f32_e32 v2, v4, v2
	v_mul_f32_e32 v4, 0xbfb8aa3b, v11
	v_exp_f32_e32 v4, v4
	s_nop 0
	v_add_f32_e32 v4, 1.0, v4
	v_rcp_f32_e32 v4, v4
	s_nop 0
	v_mul_f32_e32 v4, v11, v4
	v_mul_f32_e32 v0, v4, v0
	v_cvt_pk_bf16_f32 v67, v2, v0
	v_add_u32_e32 v0, 0x79000, v56
	v_lshl_add_u64 v[0:1], v[0:1], 1, s[4:5]
	global_store_dwordx4 v[0:1], v[64:67], off
